# SP1-only load priority (only the 16-read load segments at s_setprio 1) + packed SwiGLU epilogue
# baseline (speedup 1.0000x reference)
; #define PG8_STAGE(bufoff, gbase, voff) do { _Pragma("unroll") for (int _i = 0; _i < 2; ++_i) \
;         __builtin_amdgcn_global_load_lds((const unsigned*)((const char*)(gbase) + (voff)[_i]), (PG8_LAS unsigned*)(lds + (bufoff) + ldsw + _i * 8192), 16, 0, 0); } while (0)
; #define PG8_LDA(dst, b, h) do { _Pragma("unroll") for (int m = 0; m < 4; ++m) _Pragma("unroll") for (int k = 0; k < 2; ++k) dst[m][k] = *(const PG8_LAS bf16x8*)(lds + PG8_SA(b, h) + aoff + m * 2048 + k * 1024); } while (0)
; #define PG8_LDB(dst, b, h) do { _Pragma("unroll") for (int n = 0; n < 2; ++n) _Pragma("unroll") for (int k = 0; k < 2; ++k) dst[n][k] = *(const PG8_LAS bf16x8*)(lds + PG8_SB(b, h) + boff + n * 2048 + k * 1024); } while (0)
; #define PG8_MMA(ai, bj, At, Bt) do { __builtin_amdgcn_s_setprio(1); _Pragma("unroll") for (int m = 0; m < 4; ++m) _Pragma("unroll") for (int n = 0; n < 2; ++n) _Pragma("unroll") for (int k = 0; k < 2; ++k) \
;         acc[ai][bj][m][n] = __builtin_amdgcn_mfma_f32_16x16x32_bf16(Bt[n][k], At[m][k], acc[ai][bj][m][n], 0, 0, 0); __builtin_amdgcn_s_setprio(0); } while (0)
; #define PG8_WAIT_V(n) asm volatile("s_waitcnt vmcnt(" #n ")" ::: "memory")
; #define PG8_WAIT_L(n) asm volatile("s_waitcnt lgkmcnt(" #n ")" ::: "memory")
; #define PG8_BAR __builtin_amdgcn_s_barrier()
; #define PG8_SCHED __builtin_amdgcn_sched_barrier(0)
; template <class Epi, class Sched, bool ALIGN_EPI = false, bool SP2 = false>
; __device__ __forceinline__ void gemm_phase(PG8_LAS unsigned char* lds, const Gemm g, const Sched& S, const Epi& E, int tid_in) {
;     ...
;             PG8_LDB(B0, 0, 0); PG8_LDB(B1, 0, 1); PG8_SCHED; PG8_LDA(At, 0, 0); PG8_STAGE(PG8_SA(1, 1), a1 + hstep, voffA);
;             PG8_WAIT_V(8); PG8_WAIT_L(0); PG8_BAR; PG8_MMA(0, 0, At, B0); PG8_MMA(0, 1, At, B1); PG8_BAR; PG8_SCHED;
;             PG8_LDA(At, 0, 1); PG8_STAGE(PG8_SB(0, 0), b2, voffB); PG8_STAGE(PG8_SB(0, 1), b2 + hstep, voffB); PG8_STAGE(PG8_SA(0, 0), a2, voffA);
;             PG8_WAIT_V(8); PG8_WAIT_L(0); PG8_BAR; PG8_MMA(1, 0, At, B0); PG8_MMA(1, 1, At, B1); PG8_BAR; PG8_SCHED;
.LBB0_110:
	s_cmp_eq_u32 s11, 28
	s_cselect_b64 vcc, -1, 0
	s_add_i32 s13, 0, 0x10000
	s_add_i32 s14, 0, 0x14000
	v_lshl_add_u64 v[176:177], v[166:167], 0, s[52:53]
	v_add_u32_e32 v188, s13, v168
	v_add_u32_e32 v204, s14, v168
	v_cndmask_b32_e32 v241, v177, v131, vcc
	v_cndmask_b32_e32 v240, v176, v160, vcc
	ds_read_b128 v[176:179], v188
	ds_read_b128 v[180:183], v188 offset:1024
	ds_read_b128 v[184:187], v188 offset:2048
	ds_read_b128 v[188:191], v188 offset:3072
	ds_read_b128 v[192:195], v204
	ds_read_b128 v[196:199], v204 offset:1024
	ds_read_b128 v[200:203], v204 offset:2048
	ds_read_b128 v[204:207], v204 offset:3072
	v_cndmask_b32_e32 v243, v165, v161, vcc
	v_cndmask_b32_e32 v242, v164, v162, vcc
	v_lshl_add_u64 v[244:245], v[166:167], 0, v[154:155]
	s_add_i32 m0, s18, 0xc000
	ds_read_b128 v[208:211], v175
	ds_read_b128 v[212:215], v175 offset:1024
	ds_read_b128 v[216:219], v175 offset:2048
	ds_read_b128 v[220:223], v175 offset:3072
	ds_read_b128 v[224:227], v175 offset:4096
	ds_read_b128 v[228:231], v175 offset:5120
	ds_read_b128 v[232:235], v175 offset:6144
	ds_read_b128 v[236:239], v175 offset:7168
	global_load_lds_dwordx4 v[244:245], off
	v_lshl_add_u64 v[244:245], v[166:167], 0, v[152:153]
	s_add_i32 m0, s18, 0xe000
	s_nop 0
	global_load_lds_dwordx4 v[244:245], off
	s_setprio 0
	s_waitcnt vmcnt(8) lgkmcnt(0)
	s_barrier
	v_mfma_f32_16x16x32_bf16 v[124:127], v[176:179], v[208:211], v[124:127]
	v_mfma_f32_16x16x32_bf16 v[120:123], v[184:187], v[208:211], v[120:123]
	v_mfma_f32_16x16x32_bf16 v[116:119], v[176:179], v[216:219], v[116:119]
	v_mfma_f32_16x16x32_bf16 v[108:111], v[184:187], v[216:219], v[108:111]
	v_mfma_f32_16x16x32_bf16 v[100:103], v[176:179], v[224:227], v[100:103]
	v_mfma_f32_16x16x32_bf16 v[92:95], v[184:187], v[224:227], v[92:95]
	v_mfma_f32_16x16x32_bf16 v[84:87], v[176:179], v[232:235], v[84:87]
	v_mfma_f32_16x16x32_bf16 v[76:79], v[184:187], v[232:235], v[76:79]
	v_mfma_f32_16x16x32_bf16 v[124:127], v[180:183], v[212:215], v[124:127]
	v_mfma_f32_16x16x32_bf16 v[120:123], v[188:191], v[212:215], v[120:123]
	v_mfma_f32_16x16x32_bf16 v[116:119], v[180:183], v[220:223], v[116:119]
	v_mfma_f32_16x16x32_bf16 v[108:111], v[188:191], v[220:223], v[108:111]
	v_mfma_f32_16x16x32_bf16 v[100:103], v[180:183], v[228:231], v[100:103]
	v_mfma_f32_16x16x32_bf16 v[92:95], v[188:191], v[228:231], v[92:95]
	v_mfma_f32_16x16x32_bf16 v[84:87], v[180:183], v[236:239], v[84:87]
	v_mfma_f32_16x16x32_bf16 v[76:79], v[188:191], v[236:239], v[76:79]
	v_mfma_f32_16x16x32_bf16 v[112:115], v[192:195], v[208:211], v[112:115]
	v_mfma_f32_16x16x32_bf16 v[104:107], v[200:203], v[208:211], v[104:107]
	v_mfma_f32_16x16x32_bf16 v[96:99], v[192:195], v[216:219], v[96:99]
	v_mfma_f32_16x16x32_bf16 v[88:91], v[200:203], v[216:219], v[88:91]
	v_mfma_f32_16x16x32_bf16 v[80:83], v[192:195], v[224:227], v[80:83]
	v_mfma_f32_16x16x32_bf16 v[72:75], v[200:203], v[224:227], v[72:75]
	v_mfma_f32_16x16x32_bf16 v[68:71], v[192:195], v[232:235], v[68:71]
	v_mfma_f32_16x16x32_bf16 v[64:67], v[200:203], v[232:235], v[64:67]
	v_mfma_f32_16x16x32_bf16 v[112:115], v[196:199], v[212:215], v[112:115]
	v_mfma_f32_16x16x32_bf16 v[104:107], v[204:207], v[212:215], v[104:107]
	v_mfma_f32_16x16x32_bf16 v[96:99], v[196:199], v[220:223], v[96:99]
	v_mfma_f32_16x16x32_bf16 v[88:91], v[204:207], v[220:223], v[88:91]
	v_mfma_f32_16x16x32_bf16 v[80:83], v[196:199], v[228:231], v[80:83]
	v_mfma_f32_16x16x32_bf16 v[72:75], v[204:207], v[228:231], v[72:75]
	v_mfma_f32_16x16x32_bf16 v[68:71], v[196:199], v[236:239], v[68:71]
	v_mfma_f32_16x16x32_bf16 v[64:67], v[204:207], v[236:239], v[64:67]
	s_barrier
	s_add_i32 s13, s13, s0
	v_lshl_add_u64 v[244:245], v[242:243], 0, v[128:129]
	s_mov_b32 m0, s13
	ds_read_b128 v[208:211], v175 offset:16384
	ds_read_b128 v[212:215], v175 offset:17408
	ds_read_b128 v[216:219], v175 offset:18432
	ds_read_b128 v[220:223], v175 offset:19456
	ds_read_b128 v[224:227], v175 offset:20480
	ds_read_b128 v[228:231], v175 offset:21504
	ds_read_b128 v[232:235], v175 offset:22528
	ds_read_b128 v[236:239], v175 offset:23552
	global_load_lds_dwordx4 v[244:245], off
	v_lshl_add_u64 v[246:247], v[242:243], 0, v[144:145]
	s_add_i32 m0, s13, 0x2000
	v_lshl_add_u64 v[248:249], v[242:243], 0, s[98:99]
	s_add_i32 s13, s14, s0
	global_load_lds_dwordx4 v[246:247], off
	v_lshl_add_u64 v[250:251], v[248:249], 0, v[128:129]
	s_mov_b32 m0, s13
	v_lshl_add_u64 v[248:249], v[248:249], 0, v[144:145]
	global_load_lds_dwordx4 v[250:251], off
	s_add_i32 m0, s13, 0x2000
	v_lshl_add_u64 v[250:251], v[240:241], 0, v[146:147]
	global_load_lds_dwordx4 v[248:249], off
	v_lshl_add_u64 v[248:249], v[240:241], 0, v[148:149]
	s_mov_b32 m0, s18
	s_nop 0
	global_load_lds_dwordx4 v[248:249], off
	s_mov_b32 m0, s19
	s_nop 0
	global_load_lds_dwordx4 v[250:251], off
	s_waitcnt vmcnt(8) lgkmcnt(0)
	s_barrier
; #define PG8_STAGE(bufoff, gbase, voff) do { _Pragma("unroll") for (int _i = 0; _i < 2; ++_i) \
;         __builtin_amdgcn_global_load_lds((const unsigned*)((const char*)(gbase) + (voff)[_i]), (PG8_LAS unsigned*)(lds + (bufoff) + ldsw + _i * 8192), 16, 0, 0); } while (0)
; #define PG8_LDA(dst, b, h) do { _Pragma("unroll") for (int m = 0; m < 4; ++m) _Pragma("unroll") for (int k = 0; k < 2; ++k) dst[m][k] = *(const PG8_LAS bf16x8*)(lds + PG8_SA(b, h) + aoff + m * 2048 + k * 1024); } while (0)
; #define PG8_LDB(dst, b, h) do { _Pragma("unroll") for (int n = 0; n < 2; ++n) _Pragma("unroll") for (int k = 0; k < 2; ++k) dst[n][k] = *(const PG8_LAS bf16x8*)(lds + PG8_SB(b, h) + boff + n * 2048 + k * 1024); } while (0)
; #define PG8_MMA(ai, bj, At, Bt) do { __builtin_amdgcn_s_setprio(1); _Pragma("unroll") for (int m = 0; m < 4; ++m) _Pragma("unroll") for (int n = 0; n < 2; ++n) _Pragma("unroll") for (int k = 0; k < 2; ++k) \
;         acc[ai][bj][m][n] = __builtin_amdgcn_mfma_f32_16x16x32_bf16(Bt[n][k], At[m][k], acc[ai][bj][m][n], 0, 0, 0); __builtin_amdgcn_s_setprio(0); } while (0)
; #define PG8_WAIT_V(n) asm volatile("s_waitcnt vmcnt(" #n ")" ::: "memory")
; #define PG8_WAIT_L(n) asm volatile("s_waitcnt lgkmcnt(" #n ")" ::: "memory")
; #define PG8_BAR __builtin_amdgcn_s_barrier()
; #define PG8_SCHED __builtin_amdgcn_sched_barrier(0)
; template <class Epi, class Sched, bool ALIGN_EPI = false, bool SP2 = false>
; __device__ __forceinline__ void gemm_phase(PG8_LAS unsigned char* lds, const Gemm g, const Sched& S, const Epi& E, int tid_in) {
;     ...
;             PG8_WAIT_V(8); PG8_WAIT_L(0); PG8_BAR; PG8_MMA(1, 0, At, B0); PG8_MMA(1, 1, At, B1); PG8_BAR; PG8_SCHED;
;             PG8_LDB(B0, 1, 0); PG8_LDB(B1, 1, 1); PG8_SCHED; PG8_LDA(At, 1, 0); PG8_STAGE(PG8_SA(0, 1), a2 + hstep, voffA);
;             PG8_WAIT_V(8); PG8_WAIT_L(0); PG8_BAR; PG8_MMA(0, 0, At, B0); PG8_MMA(0, 1, At, B1); PG8_BAR; PG8_SCHED;
	v_mfma_f32_16x16x32_bf16 v[60:63], v[176:179], v[208:211], v[60:63]
	v_mfma_f32_16x16x32_bf16 v[56:59], v[184:187], v[208:211], v[56:59]
	v_mfma_f32_16x16x32_bf16 v[52:55], v[176:179], v[216:219], v[52:55]
	v_mfma_f32_16x16x32_bf16 v[44:47], v[184:187], v[216:219], v[44:47]
	v_mfma_f32_16x16x32_bf16 v[36:39], v[176:179], v[224:227], v[36:39]
	v_mfma_f32_16x16x32_bf16 v[28:31], v[184:187], v[224:227], v[28:31]
	v_mfma_f32_16x16x32_bf16 v[20:23], v[176:179], v[232:235], v[20:23]
	v_mfma_f32_16x16x32_bf16 v[12:15], v[184:187], v[232:235], v[12:15]
	v_mfma_f32_16x16x32_bf16 v[60:63], v[180:183], v[212:215], v[60:63]
	v_mfma_f32_16x16x32_bf16 v[56:59], v[188:191], v[212:215], v[56:59]
	v_mfma_f32_16x16x32_bf16 v[52:55], v[180:183], v[220:223], v[52:55]
	v_mfma_f32_16x16x32_bf16 v[44:47], v[188:191], v[220:223], v[44:47]
	v_mfma_f32_16x16x32_bf16 v[36:39], v[180:183], v[228:231], v[36:39]
	v_mfma_f32_16x16x32_bf16 v[28:31], v[188:191], v[228:231], v[28:31]
	v_mfma_f32_16x16x32_bf16 v[20:23], v[180:183], v[236:239], v[20:23]
	v_mfma_f32_16x16x32_bf16 v[12:15], v[188:191], v[236:239], v[12:15]
	v_mfma_f32_16x16x32_bf16 v[48:51], v[192:195], v[208:211], v[48:51]
	v_mfma_f32_16x16x32_bf16 v[40:43], v[200:203], v[208:211], v[40:43]
	v_mfma_f32_16x16x32_bf16 v[32:35], v[192:195], v[216:219], v[32:35]
	v_mfma_f32_16x16x32_bf16 v[24:27], v[200:203], v[216:219], v[24:27]
	v_mfma_f32_16x16x32_bf16 v[16:19], v[192:195], v[224:227], v[16:19]
	v_mfma_f32_16x16x32_bf16 v[8:11], v[200:203], v[224:227], v[8:11]
	v_mfma_f32_16x16x32_bf16 v[4:7], v[192:195], v[232:235], v[4:7]
	v_mfma_f32_16x16x32_bf16 v[0:3], v[200:203], v[232:235], v[0:3]
	v_mfma_f32_16x16x32_bf16 v[48:51], v[196:199], v[212:215], v[48:51]
	v_mfma_f32_16x16x32_bf16 v[40:43], v[204:207], v[212:215], v[40:43]
	v_mfma_f32_16x16x32_bf16 v[32:35], v[196:199], v[220:223], v[32:35]
	v_mfma_f32_16x16x32_bf16 v[24:27], v[204:207], v[220:223], v[24:27]
	v_mfma_f32_16x16x32_bf16 v[16:19], v[196:199], v[228:231], v[16:19]
	v_mfma_f32_16x16x32_bf16 v[8:11], v[204:207], v[228:231], v[8:11]
	v_mfma_f32_16x16x32_bf16 v[4:7], v[196:199], v[236:239], v[4:7]
	v_mfma_f32_16x16x32_bf16 v[0:3], v[204:207], v[236:239], v[0:3]
	s_barrier
	s_setprio 1
	s_add_i32 s13, 0, 0x18000
	s_add_i32 s14, 0, 0x1c000
	v_add_u32_e32 v188, s13, v168
	v_add_u32_e32 v204, s14, v168
	ds_read_b128 v[176:179], v188
	ds_read_b128 v[180:183], v188 offset:1024
	ds_read_b128 v[184:187], v188 offset:2048
	ds_read_b128 v[188:191], v188 offset:3072
	ds_read_b128 v[192:195], v204
	ds_read_b128 v[196:199], v204 offset:1024
	ds_read_b128 v[200:203], v204 offset:2048
	ds_read_b128 v[204:207], v204 offset:3072
	v_lshl_add_u64 v[240:241], v[240:241], 0, s[98:99]
	s_mov_b32 m0, s20
	v_lshl_add_u64 v[252:253], v[240:241], 0, v[148:149]
	ds_read_b128 v[208:211], v175 offset:32768
	ds_read_b128 v[212:215], v175 offset:33792
	ds_read_b128 v[216:219], v175 offset:34816
	ds_read_b128 v[220:223], v175 offset:35840
	ds_read_b128 v[224:227], v175 offset:36864
	ds_read_b128 v[228:231], v175 offset:37888
	ds_read_b128 v[232:235], v175 offset:38912
	ds_read_b128 v[236:239], v175 offset:39936
	global_load_lds_dwordx4 v[252:253], off
	v_lshl_add_u64 v[240:241], v[240:241], 0, v[146:147]
	s_mov_b32 m0, s21
	s_nop 0
	global_load_lds_dwordx4 v[240:241], off
	s_setprio 0
	s_waitcnt vmcnt(8) lgkmcnt(0)
	s_barrier
	v_mfma_f32_16x16x32_bf16 v[124:127], v[176:179], v[208:211], v[124:127]
	v_mfma_f32_16x16x32_bf16 v[120:123], v[184:187], v[208:211], v[120:123]
	v_mfma_f32_16x16x32_bf16 v[116:119], v[176:179], v[216:219], v[116:119]
	v_mfma_f32_16x16x32_bf16 v[108:111], v[184:187], v[216:219], v[108:111]
	v_mfma_f32_16x16x32_bf16 v[100:103], v[176:179], v[224:227], v[100:103]
	v_mfma_f32_16x16x32_bf16 v[92:95], v[184:187], v[224:227], v[92:95]
	v_mfma_f32_16x16x32_bf16 v[84:87], v[176:179], v[232:235], v[84:87]
	v_mfma_f32_16x16x32_bf16 v[76:79], v[184:187], v[232:235], v[76:79]
	v_mfma_f32_16x16x32_bf16 v[124:127], v[180:183], v[212:215], v[124:127]
	v_mfma_f32_16x16x32_bf16 v[120:123], v[188:191], v[212:215], v[120:123]
	v_mfma_f32_16x16x32_bf16 v[116:119], v[180:183], v[220:223], v[116:119]
	v_mfma_f32_16x16x32_bf16 v[108:111], v[188:191], v[220:223], v[108:111]
	v_mfma_f32_16x16x32_bf16 v[100:103], v[180:183], v[228:231], v[100:103]
	v_mfma_f32_16x16x32_bf16 v[92:95], v[188:191], v[228:231], v[92:95]
	v_mfma_f32_16x16x32_bf16 v[84:87], v[180:183], v[236:239], v[84:87]
	v_mfma_f32_16x16x32_bf16 v[76:79], v[188:191], v[236:239], v[76:79]
	v_mfma_f32_16x16x32_bf16 v[112:115], v[192:195], v[208:211], v[112:115]
	v_mfma_f32_16x16x32_bf16 v[104:107], v[200:203], v[208:211], v[104:107]
	v_mfma_f32_16x16x32_bf16 v[96:99], v[192:195], v[216:219], v[96:99]
	v_mfma_f32_16x16x32_bf16 v[88:91], v[200:203], v[216:219], v[88:91]
	v_mfma_f32_16x16x32_bf16 v[80:83], v[192:195], v[224:227], v[80:83]
	v_mfma_f32_16x16x32_bf16 v[72:75], v[200:203], v[224:227], v[72:75]
	v_mfma_f32_16x16x32_bf16 v[68:71], v[192:195], v[232:235], v[68:71]
	v_mfma_f32_16x16x32_bf16 v[64:67], v[200:203], v[232:235], v[64:67]
	v_mfma_f32_16x16x32_bf16 v[112:115], v[196:199], v[212:215], v[112:115]
	v_mfma_f32_16x16x32_bf16 v[104:107], v[204:207], v[212:215], v[104:107]
	v_mfma_f32_16x16x32_bf16 v[96:99], v[196:199], v[220:223], v[96:99]
	v_mfma_f32_16x16x32_bf16 v[88:91], v[204:207], v[220:223], v[88:91]
	v_mfma_f32_16x16x32_bf16 v[80:83], v[196:199], v[228:231], v[80:83]
	v_mfma_f32_16x16x32_bf16 v[72:75], v[204:207], v[228:231], v[72:75]
	v_mfma_f32_16x16x32_bf16 v[68:71], v[196:199], v[236:239], v[68:71]
	v_mfma_f32_16x16x32_bf16 v[64:67], v[204:207], v[236:239], v[64:67]
	s_barrier
; #define PG8_STAGE(bufoff, gbase, voff) do { _Pragma("unroll") for (int _i = 0; _i < 2; ++_i) \
;         __builtin_amdgcn_global_load_lds((const unsigned*)((const char*)(gbase) + (voff)[_i]), (PG8_LAS unsigned*)(lds + (bufoff) + ldsw + _i * 8192), 16, 0, 0); } while (0)
; #define PG8_LDA(dst, b, h) do { _Pragma("unroll") for (int m = 0; m < 4; ++m) _Pragma("unroll") for (int k = 0; k < 2; ++k) dst[m][k] = *(const PG8_LAS bf16x8*)(lds + PG8_SA(b, h) + aoff + m * 2048 + k * 1024); } while (0)
; #define PG8_MMA(ai, bj, At, Bt) do { __builtin_amdgcn_s_setprio(1); _Pragma("unroll") for (int m = 0; m < 4; ++m) _Pragma("unroll") for (int n = 0; n < 2; ++n) _Pragma("unroll") for (int k = 0; k < 2; ++k) \
;         acc[ai][bj][m][n] = __builtin_amdgcn_mfma_f32_16x16x32_bf16(Bt[n][k], At[m][k], acc[ai][bj][m][n], 0, 0, 0); __builtin_amdgcn_s_setprio(0); } while (0)
; #define PG8_WAIT_V(n) asm volatile("s_waitcnt vmcnt(" #n ")" ::: "memory")
; #define PG8_WAIT_L(n) asm volatile("s_waitcnt lgkmcnt(" #n ")" ::: "memory")
; #define PG8_BAR __builtin_amdgcn_s_barrier()
; #define PG8_SCHED __builtin_amdgcn_sched_barrier(0)
; template <class Epi, class Sched, bool ALIGN_EPI = false, bool SP2 = false>
; __device__ __forceinline__ void gemm_phase(PG8_LAS unsigned char* lds, const Gemm g, const Sched& S, const Epi& E, int tid_in) {
;     ...
;         for (int t = 0; t < nt; t += 2) {
;             const bool last = (t == nt - 2);
;             const char* a1 = cA + (size_t)(t + 1) * kstep;
;             const char* a2 = last ? nA : cA + (size_t)(t + 2) * kstep; const char* b2 = last ? nB : cB + (size_t)(t + 2) * kstep;
;             const char* a3 = a2 + kstep; const char* b3 = b2 + kstep;
;     ...
;             PG8_LDA(At, 1, 1); PG8_STAGE(PG8_SB(1, 0), b3, voffB); PG8_STAGE(PG8_SB(1, 1), b3 + hstep, voffB); PG8_STAGE(PG8_SA(1, 0), a3, voffA);
;             PG8_WAIT_V(8); PG8_WAIT_L(0); PG8_BAR; PG8_MMA(1, 0, At, B0); PG8_MMA(1, 1, At, B1); PG8_BAR; PG8_SCHED;
	s_add_i32 s13, s13, s0
	v_lshl_add_u64 v[240:241], v[244:245], 0, s[70:71]
	s_mov_b32 m0, s13
	ds_read_b128 v[208:211], v175 offset:49152
	ds_read_b128 v[212:215], v175 offset:50176
	ds_read_b128 v[216:219], v175 offset:51200
	ds_read_b128 v[220:223], v175 offset:52224
	ds_read_b128 v[224:227], v175 offset:53248
	ds_read_b128 v[228:231], v175 offset:54272
	ds_read_b128 v[232:235], v175 offset:55296
	ds_read_b128 v[236:239], v175 offset:56320
	global_load_lds_dwordx4 v[240:241], off
	v_lshl_add_u64 v[240:241], v[246:247], 0, s[70:71]
	s_add_i32 m0, s13, 0x2000
	s_add_i32 s13, s14, s0
	global_load_lds_dwordx4 v[240:241], off
	v_lshl_add_u64 v[240:241], v[242:243], 0, s[86:87]
	v_lshl_add_u64 v[242:243], v[240:241], 0, v[128:129]
	s_mov_b32 m0, s13
	v_lshl_add_u64 v[240:241], v[240:241], 0, v[144:145]
	global_load_lds_dwordx4 v[242:243], off
	s_add_i32 m0, s13, 0x2000
	s_nop 0
	global_load_lds_dwordx4 v[240:241], off
	v_lshl_add_u64 v[240:241], v[248:249], 0, s[70:71]
	s_mov_b32 m0, s22
	s_nop 0
	global_load_lds_dwordx4 v[240:241], off
	v_lshl_add_u64 v[240:241], v[250:251], 0, s[70:71]
	s_mov_b32 m0, s23
	s_nop 0
	global_load_lds_dwordx4 v[240:241], off
	s_waitcnt vmcnt(8) lgkmcnt(0)
	s_barrier
	v_mfma_f32_16x16x32_bf16 v[60:63], v[176:179], v[208:211], v[60:63]
	v_mfma_f32_16x16x32_bf16 v[56:59], v[184:187], v[208:211], v[56:59]
	v_mfma_f32_16x16x32_bf16 v[52:55], v[176:179], v[216:219], v[52:55]
	v_mfma_f32_16x16x32_bf16 v[44:47], v[184:187], v[216:219], v[44:47]
	v_mfma_f32_16x16x32_bf16 v[36:39], v[176:179], v[224:227], v[36:39]
	v_mfma_f32_16x16x32_bf16 v[28:31], v[184:187], v[224:227], v[28:31]
	v_mfma_f32_16x16x32_bf16 v[20:23], v[176:179], v[232:235], v[20:23]
	v_mfma_f32_16x16x32_bf16 v[12:15], v[184:187], v[232:235], v[12:15]
	v_mfma_f32_16x16x32_bf16 v[60:63], v[180:183], v[212:215], v[60:63]
	v_mfma_f32_16x16x32_bf16 v[56:59], v[188:191], v[212:215], v[56:59]
	v_mfma_f32_16x16x32_bf16 v[52:55], v[180:183], v[220:223], v[52:55]
	v_mfma_f32_16x16x32_bf16 v[44:47], v[188:191], v[220:223], v[44:47]
	v_mfma_f32_16x16x32_bf16 v[36:39], v[180:183], v[228:231], v[36:39]
	v_mfma_f32_16x16x32_bf16 v[28:31], v[188:191], v[228:231], v[28:31]
	v_mfma_f32_16x16x32_bf16 v[20:23], v[180:183], v[236:239], v[20:23]
	v_mfma_f32_16x16x32_bf16 v[12:15], v[188:191], v[236:239], v[12:15]
	v_mfma_f32_16x16x32_bf16 v[48:51], v[192:195], v[208:211], v[48:51]
	v_mfma_f32_16x16x32_bf16 v[40:43], v[200:203], v[208:211], v[40:43]
	v_mfma_f32_16x16x32_bf16 v[32:35], v[192:195], v[216:219], v[32:35]
	v_mfma_f32_16x16x32_bf16 v[24:27], v[200:203], v[216:219], v[24:27]
	v_mfma_f32_16x16x32_bf16 v[16:19], v[192:195], v[224:227], v[16:19]
	v_mfma_f32_16x16x32_bf16 v[8:11], v[200:203], v[224:227], v[8:11]
	v_mfma_f32_16x16x32_bf16 v[4:7], v[192:195], v[232:235], v[4:7]
	v_mfma_f32_16x16x32_bf16 v[0:3], v[200:203], v[232:235], v[0:3]
	v_mfma_f32_16x16x32_bf16 v[48:51], v[196:199], v[212:215], v[48:51]
	v_mfma_f32_16x16x32_bf16 v[40:43], v[204:207], v[212:215], v[40:43]
	v_mfma_f32_16x16x32_bf16 v[32:35], v[196:199], v[220:223], v[32:35]
	v_mfma_f32_16x16x32_bf16 v[24:27], v[204:207], v[220:223], v[24:27]
	v_mfma_f32_16x16x32_bf16 v[16:19], v[196:199], v[228:231], v[16:19]
	v_mfma_f32_16x16x32_bf16 v[8:11], v[204:207], v[228:231], v[8:11]
	v_mfma_f32_16x16x32_bf16 v[4:7], v[196:199], v[236:239], v[4:7]
	v_mfma_f32_16x16x32_bf16 v[0:3], v[204:207], v[236:239], v[0:3]
	s_barrier
	s_setprio 1
	s_add_i32 s11, s11, 2
	v_lshl_add_u64 v[164:165], v[164:165], 0, s[82:83]
	s_cmp_gt_u32 s11, 29
	v_lshl_add_u64 v[166:167], v[166:167], 0, s[82:83]
	s_cbranch_scc0 .LBB0_110
	s_setprio 0
	s_and_b64 vcc, exec, s[8:9]
	s_cbranch_vccz .LBB0_113
	s_barrier

; #define PG8_STAGE(bufoff, gbase, voff) do { _Pragma("unroll") for (int _i = 0; _i < 2; ++_i) \
;         __builtin_amdgcn_global_load_lds((const unsigned*)((const char*)(gbase) + (voff)[_i]), (PG8_LAS unsigned*)(lds + (bufoff) + ldsw + _i * 8192), 16, 0, 0); } while (0)
; #define PG8_LDA(dst, b, h) do { _Pragma("unroll") for (int m = 0; m < 4; ++m) _Pragma("unroll") for (int k = 0; k < 2; ++k) dst[m][k] = *(const PG8_LAS bf16x8*)(lds + PG8_SA(b, h) + aoff + m * 2048 + k * 1024); } while (0)
; #define PG8_LDB(dst, b, h) do { _Pragma("unroll") for (int n = 0; n < 2; ++n) _Pragma("unroll") for (int k = 0; k < 2; ++k) dst[n][k] = *(const PG8_LAS bf16x8*)(lds + PG8_SB(b, h) + boff + n * 2048 + k * 1024); } while (0)
; #define PG8_MMA(ai, bj, At, Bt) do { __builtin_amdgcn_s_setprio(1); _Pragma("unroll") for (int m = 0; m < 4; ++m) _Pragma("unroll") for (int n = 0; n < 2; ++n) _Pragma("unroll") for (int k = 0; k < 2; ++k) \
;         acc[ai][bj][m][n] = __builtin_amdgcn_mfma_f32_16x16x32_bf16(Bt[n][k], At[m][k], acc[ai][bj][m][n], 0, 0, 0); __builtin_amdgcn_s_setprio(0); } while (0)
; #define PG8_WAIT_V(n) asm volatile("s_waitcnt vmcnt(" #n ")" ::: "memory")
; #define PG8_WAIT_L(n) asm volatile("s_waitcnt lgkmcnt(" #n ")" ::: "memory")
; #define PG8_BAR __builtin_amdgcn_s_barrier()
; #define PG8_SCHED __builtin_amdgcn_sched_barrier(0)
; template <class Epi, class Sched, bool ALIGN_EPI = false, bool SP2 = false>
; __device__ __forceinline__ void gemm_phase(PG8_LAS unsigned char* lds, const Gemm g, const Sched& S, const Epi& E, int tid_in) {
;     ...
;             PG8_LDB(B0, 0, 0); PG8_LDB(B1, 0, 1); PG8_SCHED; PG8_LDA(At, 0, 0); PG8_STAGE(PG8_SA(1, 1), a1 + hstep, voffA);
;             PG8_WAIT_V(8); PG8_WAIT_L(0); PG8_BAR; PG8_MMA(0, 0, At, B0); PG8_MMA(0, 1, At, B1); PG8_BAR; PG8_SCHED;
;             PG8_LDA(At, 0, 1); PG8_STAGE(PG8_SB(0, 0), b2, voffB); PG8_STAGE(PG8_SB(0, 1), b2 + hstep, voffB); PG8_STAGE(PG8_SA(0, 0), a2, voffA);
;             PG8_WAIT_V(8); PG8_WAIT_L(0); PG8_BAR; PG8_MMA(1, 0, At, B0); PG8_MMA(1, 1, At, B1); PG8_BAR; PG8_SCHED;
.LBB0_405:
	s_cmp_eq_u32 s2, 28
	s_cselect_b64 vcc, -1, 0
	s_add_i32 s3, 0, 0x10000
	s_add_i32 s13, 0, 0x14000
	v_lshl_add_u64 v[176:177], v[166:167], 0, s[52:53]
	v_add_u32_e32 v188, s3, v168
	v_add_u32_e32 v204, s13, v168
	v_cndmask_b32_e32 v241, v177, v131, vcc
	v_cndmask_b32_e32 v240, v176, v160, vcc
	ds_read_b128 v[176:179], v188
	ds_read_b128 v[180:183], v188 offset:1024
	ds_read_b128 v[184:187], v188 offset:2048
	ds_read_b128 v[188:191], v188 offset:3072
	ds_read_b128 v[192:195], v204
	ds_read_b128 v[196:199], v204 offset:1024
	ds_read_b128 v[200:203], v204 offset:2048
	ds_read_b128 v[204:207], v204 offset:3072
	v_cndmask_b32_e32 v243, v165, v161, vcc
	v_cndmask_b32_e32 v242, v164, v162, vcc
	v_lshl_add_u64 v[244:245], v[166:167], 0, v[154:155]
	s_add_i32 m0, s16, 0xc000
	ds_read_b128 v[208:211], v175
	ds_read_b128 v[212:215], v175 offset:1024
	ds_read_b128 v[216:219], v175 offset:2048
	ds_read_b128 v[220:223], v175 offset:3072
	ds_read_b128 v[224:227], v175 offset:4096
	ds_read_b128 v[228:231], v175 offset:5120
	ds_read_b128 v[232:235], v175 offset:6144
	ds_read_b128 v[236:239], v175 offset:7168
	global_load_lds_dwordx4 v[244:245], off
	v_lshl_add_u64 v[244:245], v[166:167], 0, v[152:153]
	s_add_i32 m0, s16, 0xe000
	s_nop 0
	global_load_lds_dwordx4 v[244:245], off
	s_setprio 0
	s_waitcnt vmcnt(8) lgkmcnt(0)
	s_barrier
	v_mfma_f32_16x16x32_bf16 v[124:127], v[176:179], v[208:211], v[124:127]
	v_mfma_f32_16x16x32_bf16 v[120:123], v[184:187], v[208:211], v[120:123]
	v_mfma_f32_16x16x32_bf16 v[116:119], v[176:179], v[216:219], v[116:119]
	v_mfma_f32_16x16x32_bf16 v[108:111], v[184:187], v[216:219], v[108:111]
	v_mfma_f32_16x16x32_bf16 v[100:103], v[176:179], v[224:227], v[100:103]
	v_mfma_f32_16x16x32_bf16 v[92:95], v[184:187], v[224:227], v[92:95]
	v_mfma_f32_16x16x32_bf16 v[84:87], v[176:179], v[232:235], v[84:87]
	v_mfma_f32_16x16x32_bf16 v[76:79], v[184:187], v[232:235], v[76:79]
	v_mfma_f32_16x16x32_bf16 v[124:127], v[180:183], v[212:215], v[124:127]
	v_mfma_f32_16x16x32_bf16 v[120:123], v[188:191], v[212:215], v[120:123]
	v_mfma_f32_16x16x32_bf16 v[116:119], v[180:183], v[220:223], v[116:119]
	v_mfma_f32_16x16x32_bf16 v[108:111], v[188:191], v[220:223], v[108:111]
	v_mfma_f32_16x16x32_bf16 v[100:103], v[180:183], v[228:231], v[100:103]
	v_mfma_f32_16x16x32_bf16 v[92:95], v[188:191], v[228:231], v[92:95]
	v_mfma_f32_16x16x32_bf16 v[84:87], v[180:183], v[236:239], v[84:87]
	v_mfma_f32_16x16x32_bf16 v[76:79], v[188:191], v[236:239], v[76:79]
	v_mfma_f32_16x16x32_bf16 v[112:115], v[192:195], v[208:211], v[112:115]
	v_mfma_f32_16x16x32_bf16 v[104:107], v[200:203], v[208:211], v[104:107]
	v_mfma_f32_16x16x32_bf16 v[96:99], v[192:195], v[216:219], v[96:99]
	v_mfma_f32_16x16x32_bf16 v[88:91], v[200:203], v[216:219], v[88:91]
	v_mfma_f32_16x16x32_bf16 v[80:83], v[192:195], v[224:227], v[80:83]
	v_mfma_f32_16x16x32_bf16 v[72:75], v[200:203], v[224:227], v[72:75]
	v_mfma_f32_16x16x32_bf16 v[68:71], v[192:195], v[232:235], v[68:71]
	v_mfma_f32_16x16x32_bf16 v[64:67], v[200:203], v[232:235], v[64:67]
	v_mfma_f32_16x16x32_bf16 v[112:115], v[196:199], v[212:215], v[112:115]
	v_mfma_f32_16x16x32_bf16 v[104:107], v[204:207], v[212:215], v[104:107]
	v_mfma_f32_16x16x32_bf16 v[96:99], v[196:199], v[220:223], v[96:99]
	v_mfma_f32_16x16x32_bf16 v[88:91], v[204:207], v[220:223], v[88:91]
	v_mfma_f32_16x16x32_bf16 v[80:83], v[196:199], v[228:231], v[80:83]
	v_mfma_f32_16x16x32_bf16 v[72:75], v[204:207], v[228:231], v[72:75]
	v_mfma_f32_16x16x32_bf16 v[68:71], v[196:199], v[236:239], v[68:71]
	v_mfma_f32_16x16x32_bf16 v[64:67], v[204:207], v[236:239], v[64:67]
	s_barrier
	s_add_i32 s3, s3, s1
	v_lshl_add_u64 v[244:245], v[242:243], 0, v[128:129]
	s_mov_b32 m0, s3
	ds_read_b128 v[208:211], v175 offset:16384
	ds_read_b128 v[212:215], v175 offset:17408
	ds_read_b128 v[216:219], v175 offset:18432
	ds_read_b128 v[220:223], v175 offset:19456
	ds_read_b128 v[224:227], v175 offset:20480
	ds_read_b128 v[228:231], v175 offset:21504
	ds_read_b128 v[232:235], v175 offset:22528
	ds_read_b128 v[236:239], v175 offset:23552
	global_load_lds_dwordx4 v[244:245], off
	v_lshl_add_u64 v[246:247], v[242:243], 0, v[144:145]
	s_add_i32 m0, s3, 0x2000
	v_lshl_add_u64 v[248:249], v[242:243], 0, s[98:99]
	s_add_i32 s3, s13, s1
	global_load_lds_dwordx4 v[246:247], off
	v_lshl_add_u64 v[250:251], v[248:249], 0, v[128:129]
	s_mov_b32 m0, s3
	v_lshl_add_u64 v[248:249], v[248:249], 0, v[144:145]
	global_load_lds_dwordx4 v[250:251], off
	s_add_i32 m0, s3, 0x2000
	v_lshl_add_u64 v[250:251], v[240:241], 0, v[146:147]
	global_load_lds_dwordx4 v[248:249], off
	v_lshl_add_u64 v[248:249], v[240:241], 0, v[148:149]
	s_mov_b32 m0, s16
	s_nop 0
	global_load_lds_dwordx4 v[248:249], off
	s_mov_b32 m0, s17
	s_nop 0
	global_load_lds_dwordx4 v[250:251], off
	s_waitcnt vmcnt(8) lgkmcnt(0)
	s_barrier
; #define PG8_STAGE(bufoff, gbase, voff) do { _Pragma("unroll") for (int _i = 0; _i < 2; ++_i) \
;         __builtin_amdgcn_global_load_lds((const unsigned*)((const char*)(gbase) + (voff)[_i]), (PG8_LAS unsigned*)(lds + (bufoff) + ldsw + _i * 8192), 16, 0, 0); } while (0)
; #define PG8_LDA(dst, b, h) do { _Pragma("unroll") for (int m = 0; m < 4; ++m) _Pragma("unroll") for (int k = 0; k < 2; ++k) dst[m][k] = *(const PG8_LAS bf16x8*)(lds + PG8_SA(b, h) + aoff + m * 2048 + k * 1024); } while (0)
; #define PG8_LDB(dst, b, h) do { _Pragma("unroll") for (int n = 0; n < 2; ++n) _Pragma("unroll") for (int k = 0; k < 2; ++k) dst[n][k] = *(const PG8_LAS bf16x8*)(lds + PG8_SB(b, h) + boff + n * 2048 + k * 1024); } while (0)
; #define PG8_MMA(ai, bj, At, Bt) do { __builtin_amdgcn_s_setprio(1); _Pragma("unroll") for (int m = 0; m < 4; ++m) _Pragma("unroll") for (int n = 0; n < 2; ++n) _Pragma("unroll") for (int k = 0; k < 2; ++k) \
;         acc[ai][bj][m][n] = __builtin_amdgcn_mfma_f32_16x16x32_bf16(Bt[n][k], At[m][k], acc[ai][bj][m][n], 0, 0, 0); __builtin_amdgcn_s_setprio(0); } while (0)
; #define PG8_WAIT_V(n) asm volatile("s_waitcnt vmcnt(" #n ")" ::: "memory")
; #define PG8_WAIT_L(n) asm volatile("s_waitcnt lgkmcnt(" #n ")" ::: "memory")
; #define PG8_BAR __builtin_amdgcn_s_barrier()
; #define PG8_SCHED __builtin_amdgcn_sched_barrier(0)
; template <class Epi, class Sched, bool ALIGN_EPI = false, bool SP2 = false>
; __device__ __forceinline__ void gemm_phase(PG8_LAS unsigned char* lds, const Gemm g, const Sched& S, const Epi& E, int tid_in) {
;     ...
;             PG8_WAIT_V(8); PG8_WAIT_L(0); PG8_BAR; PG8_MMA(1, 0, At, B0); PG8_MMA(1, 1, At, B1); PG8_BAR; PG8_SCHED;
;             PG8_LDB(B0, 1, 0); PG8_LDB(B1, 1, 1); PG8_SCHED; PG8_LDA(At, 1, 0); PG8_STAGE(PG8_SA(0, 1), a2 + hstep, voffA);
;             PG8_WAIT_V(8); PG8_WAIT_L(0); PG8_BAR; PG8_MMA(0, 0, At, B0); PG8_MMA(0, 1, At, B1); PG8_BAR; PG8_SCHED;
	v_mfma_f32_16x16x32_bf16 v[60:63], v[176:179], v[208:211], v[60:63]
	v_mfma_f32_16x16x32_bf16 v[56:59], v[184:187], v[208:211], v[56:59]
	v_mfma_f32_16x16x32_bf16 v[52:55], v[176:179], v[216:219], v[52:55]
	v_mfma_f32_16x16x32_bf16 v[44:47], v[184:187], v[216:219], v[44:47]
	v_mfma_f32_16x16x32_bf16 v[36:39], v[176:179], v[224:227], v[36:39]
	v_mfma_f32_16x16x32_bf16 v[28:31], v[184:187], v[224:227], v[28:31]
	v_mfma_f32_16x16x32_bf16 v[20:23], v[176:179], v[232:235], v[20:23]
	v_mfma_f32_16x16x32_bf16 v[12:15], v[184:187], v[232:235], v[12:15]
	v_mfma_f32_16x16x32_bf16 v[60:63], v[180:183], v[212:215], v[60:63]
	v_mfma_f32_16x16x32_bf16 v[56:59], v[188:191], v[212:215], v[56:59]
	v_mfma_f32_16x16x32_bf16 v[52:55], v[180:183], v[220:223], v[52:55]
	v_mfma_f32_16x16x32_bf16 v[44:47], v[188:191], v[220:223], v[44:47]
	v_mfma_f32_16x16x32_bf16 v[36:39], v[180:183], v[228:231], v[36:39]
	v_mfma_f32_16x16x32_bf16 v[28:31], v[188:191], v[228:231], v[28:31]
	v_mfma_f32_16x16x32_bf16 v[20:23], v[180:183], v[236:239], v[20:23]
	v_mfma_f32_16x16x32_bf16 v[12:15], v[188:191], v[236:239], v[12:15]
	v_mfma_f32_16x16x32_bf16 v[48:51], v[192:195], v[208:211], v[48:51]
	v_mfma_f32_16x16x32_bf16 v[40:43], v[200:203], v[208:211], v[40:43]
	v_mfma_f32_16x16x32_bf16 v[32:35], v[192:195], v[216:219], v[32:35]
	v_mfma_f32_16x16x32_bf16 v[24:27], v[200:203], v[216:219], v[24:27]
	v_mfma_f32_16x16x32_bf16 v[16:19], v[192:195], v[224:227], v[16:19]
	v_mfma_f32_16x16x32_bf16 v[8:11], v[200:203], v[224:227], v[8:11]
	v_mfma_f32_16x16x32_bf16 v[4:7], v[192:195], v[232:235], v[4:7]
	v_mfma_f32_16x16x32_bf16 v[0:3], v[200:203], v[232:235], v[0:3]
	v_mfma_f32_16x16x32_bf16 v[48:51], v[196:199], v[212:215], v[48:51]
	v_mfma_f32_16x16x32_bf16 v[40:43], v[204:207], v[212:215], v[40:43]
	v_mfma_f32_16x16x32_bf16 v[32:35], v[196:199], v[220:223], v[32:35]
	v_mfma_f32_16x16x32_bf16 v[24:27], v[204:207], v[220:223], v[24:27]
	v_mfma_f32_16x16x32_bf16 v[16:19], v[196:199], v[228:231], v[16:19]
	v_mfma_f32_16x16x32_bf16 v[8:11], v[204:207], v[228:231], v[8:11]
	v_mfma_f32_16x16x32_bf16 v[4:7], v[196:199], v[236:239], v[4:7]
	v_mfma_f32_16x16x32_bf16 v[0:3], v[204:207], v[236:239], v[0:3]
	s_barrier
	s_setprio 1
	s_add_i32 s3, 0, 0x18000
	s_add_i32 s13, 0, 0x1c000
	v_add_u32_e32 v188, s3, v168
	v_add_u32_e32 v204, s13, v168
	ds_read_b128 v[176:179], v188
	ds_read_b128 v[180:183], v188 offset:1024
	ds_read_b128 v[184:187], v188 offset:2048
	ds_read_b128 v[188:191], v188 offset:3072
	ds_read_b128 v[192:195], v204
	ds_read_b128 v[196:199], v204 offset:1024
	ds_read_b128 v[200:203], v204 offset:2048
	ds_read_b128 v[204:207], v204 offset:3072
	v_lshl_add_u64 v[240:241], v[240:241], 0, s[98:99]
	s_mov_b32 m0, s18
	v_lshl_add_u64 v[252:253], v[240:241], 0, v[148:149]
	ds_read_b128 v[208:211], v175 offset:32768
	ds_read_b128 v[212:215], v175 offset:33792
	ds_read_b128 v[216:219], v175 offset:34816
	ds_read_b128 v[220:223], v175 offset:35840
	ds_read_b128 v[224:227], v175 offset:36864
	ds_read_b128 v[228:231], v175 offset:37888
	ds_read_b128 v[232:235], v175 offset:38912
	ds_read_b128 v[236:239], v175 offset:39936
	global_load_lds_dwordx4 v[252:253], off
	v_lshl_add_u64 v[240:241], v[240:241], 0, v[146:147]
	s_mov_b32 m0, s19
	s_nop 0
	global_load_lds_dwordx4 v[240:241], off
	s_setprio 0
	s_waitcnt vmcnt(8) lgkmcnt(0)
	s_barrier
	v_mfma_f32_16x16x32_bf16 v[124:127], v[176:179], v[208:211], v[124:127]
	v_mfma_f32_16x16x32_bf16 v[120:123], v[184:187], v[208:211], v[120:123]
	v_mfma_f32_16x16x32_bf16 v[116:119], v[176:179], v[216:219], v[116:119]
	v_mfma_f32_16x16x32_bf16 v[108:111], v[184:187], v[216:219], v[108:111]
	v_mfma_f32_16x16x32_bf16 v[100:103], v[176:179], v[224:227], v[100:103]
	v_mfma_f32_16x16x32_bf16 v[92:95], v[184:187], v[224:227], v[92:95]
	v_mfma_f32_16x16x32_bf16 v[84:87], v[176:179], v[232:235], v[84:87]
	v_mfma_f32_16x16x32_bf16 v[76:79], v[184:187], v[232:235], v[76:79]
	v_mfma_f32_16x16x32_bf16 v[124:127], v[180:183], v[212:215], v[124:127]
	v_mfma_f32_16x16x32_bf16 v[120:123], v[188:191], v[212:215], v[120:123]
	v_mfma_f32_16x16x32_bf16 v[116:119], v[180:183], v[220:223], v[116:119]
	v_mfma_f32_16x16x32_bf16 v[108:111], v[188:191], v[220:223], v[108:111]
	v_mfma_f32_16x16x32_bf16 v[100:103], v[180:183], v[228:231], v[100:103]
	v_mfma_f32_16x16x32_bf16 v[92:95], v[188:191], v[228:231], v[92:95]
	v_mfma_f32_16x16x32_bf16 v[84:87], v[180:183], v[236:239], v[84:87]
	v_mfma_f32_16x16x32_bf16 v[76:79], v[188:191], v[236:239], v[76:79]
	v_mfma_f32_16x16x32_bf16 v[112:115], v[192:195], v[208:211], v[112:115]
	v_mfma_f32_16x16x32_bf16 v[104:107], v[200:203], v[208:211], v[104:107]
	v_mfma_f32_16x16x32_bf16 v[96:99], v[192:195], v[216:219], v[96:99]
	v_mfma_f32_16x16x32_bf16 v[88:91], v[200:203], v[216:219], v[88:91]
	v_mfma_f32_16x16x32_bf16 v[80:83], v[192:195], v[224:227], v[80:83]
	v_mfma_f32_16x16x32_bf16 v[72:75], v[200:203], v[224:227], v[72:75]
	v_mfma_f32_16x16x32_bf16 v[68:71], v[192:195], v[232:235], v[68:71]
	v_mfma_f32_16x16x32_bf16 v[64:67], v[200:203], v[232:235], v[64:67]
	v_mfma_f32_16x16x32_bf16 v[112:115], v[196:199], v[212:215], v[112:115]
	v_mfma_f32_16x16x32_bf16 v[104:107], v[204:207], v[212:215], v[104:107]
	v_mfma_f32_16x16x32_bf16 v[96:99], v[196:199], v[220:223], v[96:99]
	v_mfma_f32_16x16x32_bf16 v[88:91], v[204:207], v[220:223], v[88:91]
	v_mfma_f32_16x16x32_bf16 v[80:83], v[196:199], v[228:231], v[80:83]
	v_mfma_f32_16x16x32_bf16 v[72:75], v[204:207], v[228:231], v[72:75]
	v_mfma_f32_16x16x32_bf16 v[68:71], v[196:199], v[236:239], v[68:71]
	v_mfma_f32_16x16x32_bf16 v[64:67], v[204:207], v[236:239], v[64:67]
	s_barrier
; #define PG8_STAGE(bufoff, gbase, voff) do { _Pragma("unroll") for (int _i = 0; _i < 2; ++_i) \
;         __builtin_amdgcn_global_load_lds((const unsigned*)((const char*)(gbase) + (voff)[_i]), (PG8_LAS unsigned*)(lds + (bufoff) + ldsw + _i * 8192), 16, 0, 0); } while (0)
; #define PG8_LDA(dst, b, h) do { _Pragma("unroll") for (int m = 0; m < 4; ++m) _Pragma("unroll") for (int k = 0; k < 2; ++k) dst[m][k] = *(const PG8_LAS bf16x8*)(lds + PG8_SA(b, h) + aoff + m * 2048 + k * 1024); } while (0)
; #define PG8_MMA(ai, bj, At, Bt) do { __builtin_amdgcn_s_setprio(1); _Pragma("unroll") for (int m = 0; m < 4; ++m) _Pragma("unroll") for (int n = 0; n < 2; ++n) _Pragma("unroll") for (int k = 0; k < 2; ++k) \
;         acc[ai][bj][m][n] = __builtin_amdgcn_mfma_f32_16x16x32_bf16(Bt[n][k], At[m][k], acc[ai][bj][m][n], 0, 0, 0); __builtin_amdgcn_s_setprio(0); } while (0)
; #define PG8_WAIT_V(n) asm volatile("s_waitcnt vmcnt(" #n ")" ::: "memory")
; #define PG8_WAIT_L(n) asm volatile("s_waitcnt lgkmcnt(" #n ")" ::: "memory")
; #define PG8_BAR __builtin_amdgcn_s_barrier()
; #define PG8_SCHED __builtin_amdgcn_sched_barrier(0)
; template <class Epi, class Sched, bool ALIGN_EPI = false, bool SP2 = false>
; __device__ __forceinline__ void gemm_phase(PG8_LAS unsigned char* lds, const Gemm g, const Sched& S, const Epi& E, int tid_in) {
;     ...
;         for (int t = 0; t < nt; t += 2) {
;             const bool last = (t == nt - 2);
;             const char* a1 = cA + (size_t)(t + 1) * kstep;
;             const char* a2 = last ? nA : cA + (size_t)(t + 2) * kstep; const char* b2 = last ? nB : cB + (size_t)(t + 2) * kstep;
;             const char* a3 = a2 + kstep; const char* b3 = b2 + kstep;
;     ...
;             PG8_LDA(At, 1, 1); PG8_STAGE(PG8_SB(1, 0), b3, voffB); PG8_STAGE(PG8_SB(1, 1), b3 + hstep, voffB); PG8_STAGE(PG8_SA(1, 0), a3, voffA);
;             PG8_WAIT_V(8); PG8_WAIT_L(0); PG8_BAR; PG8_MMA(1, 0, At, B0); PG8_MMA(1, 1, At, B1); PG8_BAR; PG8_SCHED;
	s_add_i32 s3, s3, s1
	v_lshl_add_u64 v[240:241], v[244:245], 0, s[70:71]
	s_mov_b32 m0, s3
	ds_read_b128 v[208:211], v175 offset:49152
	ds_read_b128 v[212:215], v175 offset:50176
	ds_read_b128 v[216:219], v175 offset:51200
	ds_read_b128 v[220:223], v175 offset:52224
	ds_read_b128 v[224:227], v175 offset:53248
	ds_read_b128 v[228:231], v175 offset:54272
	ds_read_b128 v[232:235], v175 offset:55296
	ds_read_b128 v[236:239], v175 offset:56320
	global_load_lds_dwordx4 v[240:241], off
	v_lshl_add_u64 v[240:241], v[246:247], 0, s[70:71]
	s_add_i32 m0, s3, 0x2000
	s_add_i32 s3, s13, s1
	global_load_lds_dwordx4 v[240:241], off
	v_lshl_add_u64 v[240:241], v[242:243], 0, s[86:87]
	v_lshl_add_u64 v[242:243], v[240:241], 0, v[128:129]
	s_mov_b32 m0, s3
	v_lshl_add_u64 v[240:241], v[240:241], 0, v[144:145]
	global_load_lds_dwordx4 v[242:243], off
	s_add_i32 m0, s3, 0x2000
	s_nop 0
	global_load_lds_dwordx4 v[240:241], off
	v_lshl_add_u64 v[240:241], v[248:249], 0, s[70:71]
	s_mov_b32 m0, s20
	s_nop 0
	global_load_lds_dwordx4 v[240:241], off
	v_lshl_add_u64 v[240:241], v[250:251], 0, s[70:71]
	s_mov_b32 m0, s21
	s_nop 0
	global_load_lds_dwordx4 v[240:241], off
	s_waitcnt vmcnt(8) lgkmcnt(0)
	s_barrier
	v_mfma_f32_16x16x32_bf16 v[60:63], v[176:179], v[208:211], v[60:63]
	v_mfma_f32_16x16x32_bf16 v[56:59], v[184:187], v[208:211], v[56:59]
	v_mfma_f32_16x16x32_bf16 v[52:55], v[176:179], v[216:219], v[52:55]
	v_mfma_f32_16x16x32_bf16 v[44:47], v[184:187], v[216:219], v[44:47]
	v_mfma_f32_16x16x32_bf16 v[36:39], v[176:179], v[224:227], v[36:39]
	v_mfma_f32_16x16x32_bf16 v[28:31], v[184:187], v[224:227], v[28:31]
	v_mfma_f32_16x16x32_bf16 v[20:23], v[176:179], v[232:235], v[20:23]
	v_mfma_f32_16x16x32_bf16 v[12:15], v[184:187], v[232:235], v[12:15]
	v_mfma_f32_16x16x32_bf16 v[60:63], v[180:183], v[212:215], v[60:63]
	v_mfma_f32_16x16x32_bf16 v[56:59], v[188:191], v[212:215], v[56:59]
	v_mfma_f32_16x16x32_bf16 v[52:55], v[180:183], v[220:223], v[52:55]
	v_mfma_f32_16x16x32_bf16 v[44:47], v[188:191], v[220:223], v[44:47]
	v_mfma_f32_16x16x32_bf16 v[36:39], v[180:183], v[228:231], v[36:39]
	v_mfma_f32_16x16x32_bf16 v[28:31], v[188:191], v[228:231], v[28:31]
	v_mfma_f32_16x16x32_bf16 v[20:23], v[180:183], v[236:239], v[20:23]
	v_mfma_f32_16x16x32_bf16 v[12:15], v[188:191], v[236:239], v[12:15]
	v_mfma_f32_16x16x32_bf16 v[48:51], v[192:195], v[208:211], v[48:51]
	v_mfma_f32_16x16x32_bf16 v[40:43], v[200:203], v[208:211], v[40:43]
	v_mfma_f32_16x16x32_bf16 v[32:35], v[192:195], v[216:219], v[32:35]
	v_mfma_f32_16x16x32_bf16 v[24:27], v[200:203], v[216:219], v[24:27]
	v_mfma_f32_16x16x32_bf16 v[16:19], v[192:195], v[224:227], v[16:19]
	v_mfma_f32_16x16x32_bf16 v[8:11], v[200:203], v[224:227], v[8:11]
	v_mfma_f32_16x16x32_bf16 v[4:7], v[192:195], v[232:235], v[4:7]
	v_mfma_f32_16x16x32_bf16 v[0:3], v[200:203], v[232:235], v[0:3]
	v_mfma_f32_16x16x32_bf16 v[48:51], v[196:199], v[212:215], v[48:51]
	v_mfma_f32_16x16x32_bf16 v[40:43], v[204:207], v[212:215], v[40:43]
	v_mfma_f32_16x16x32_bf16 v[32:35], v[196:199], v[220:223], v[32:35]
	v_mfma_f32_16x16x32_bf16 v[24:27], v[204:207], v[220:223], v[24:27]
	v_mfma_f32_16x16x32_bf16 v[16:19], v[196:199], v[228:231], v[16:19]
	v_mfma_f32_16x16x32_bf16 v[8:11], v[204:207], v[228:231], v[8:11]
	v_mfma_f32_16x16x32_bf16 v[4:7], v[196:199], v[236:239], v[4:7]
	v_mfma_f32_16x16x32_bf16 v[0:3], v[204:207], v[236:239], v[0:3]
	s_barrier
	s_setprio 1
	s_add_i32 s2, s2, 2
	v_lshl_add_u64 v[164:165], v[164:165], 0, s[82:83]
	s_cmp_gt_u32 s2, 29
	v_lshl_add_u64 v[166:167], v[166:167], 0, s[82:83]
	s_cbranch_scc0 .LBB0_405
	s_setprio 0
	s_and_b64 vcc, exec, s[10:11]
	s_cbranch_vccz .LBB0_408
	s_barrier

; #define PG8_STAGE(bufoff, gbase, voff) do { _Pragma("unroll") for (int _i = 0; _i < 2; ++_i) \
;         __builtin_amdgcn_global_load_lds((const unsigned*)((const char*)(gbase) + (voff)[_i]), (PG8_LAS unsigned*)(lds + (bufoff) + ldsw + _i * 8192), 16, 0, 0); } while (0)
; #define PG8_LDA(dst, b, h) do { _Pragma("unroll") for (int m = 0; m < 4; ++m) _Pragma("unroll") for (int k = 0; k < 2; ++k) dst[m][k] = *(const PG8_LAS bf16x8*)(lds + PG8_SA(b, h) + aoff + m * 2048 + k * 1024); } while (0)
; #define PG8_LDB(dst, b, h) do { _Pragma("unroll") for (int n = 0; n < 2; ++n) _Pragma("unroll") for (int k = 0; k < 2; ++k) dst[n][k] = *(const PG8_LAS bf16x8*)(lds + PG8_SB(b, h) + boff + n * 2048 + k * 1024); } while (0)
; #define PG8_MMA(ai, bj, At, Bt) do { __builtin_amdgcn_s_setprio(1); _Pragma("unroll") for (int m = 0; m < 4; ++m) _Pragma("unroll") for (int n = 0; n < 2; ++n) _Pragma("unroll") for (int k = 0; k < 2; ++k) \
;         acc[ai][bj][m][n] = __builtin_amdgcn_mfma_f32_16x16x32_bf16(Bt[n][k], At[m][k], acc[ai][bj][m][n], 0, 0, 0); __builtin_amdgcn_s_setprio(0); } while (0)
; #define PG8_WAIT_V(n) asm volatile("s_waitcnt vmcnt(" #n ")" ::: "memory")
; #define PG8_WAIT_L(n) asm volatile("s_waitcnt lgkmcnt(" #n ")" ::: "memory")
; #define PG8_BAR __builtin_amdgcn_s_barrier()
; #define PG8_SCHED __builtin_amdgcn_sched_barrier(0)
; template <class Epi, class Sched, bool ALIGN_EPI = false, bool SP2 = false>
; __device__ __forceinline__ void gemm_phase(PG8_LAS unsigned char* lds, const Gemm g, const Sched& S, const Epi& E, int tid_in) {
;     ...
;             PG8_LDB(B0, 0, 0); PG8_LDB(B1, 0, 1); PG8_SCHED; PG8_LDA(At, 0, 0); PG8_STAGE(PG8_SA(1, 1), a1 + hstep, voffA);
;             PG8_WAIT_V(8); PG8_WAIT_L(0); PG8_BAR; PG8_MMA(0, 0, At, B0); PG8_MMA(0, 1, At, B1); PG8_BAR; PG8_SCHED;
;             PG8_LDA(At, 0, 1); PG8_STAGE(PG8_SB(0, 0), b2, voffB); PG8_STAGE(PG8_SB(0, 1), b2 + hstep, voffB); PG8_STAGE(PG8_SA(0, 0), a2, voffA);
;             PG8_WAIT_V(8); PG8_WAIT_L(0); PG8_BAR; PG8_MMA(1, 0, At, B0); PG8_MMA(1, 1, At, B1); PG8_BAR; PG8_SCHED;
.LBB0_588:
	s_cmp_eq_u32 s2, 28
	s_cselect_b64 vcc, -1, 0
	s_add_i32 s3, 0, 0x10000
	s_add_i32 s11, 0, 0x14000
	v_lshl_add_u64 v[176:177], v[166:167], 0, s[52:53]
	v_add_u32_e32 v188, s3, v168
	v_add_u32_e32 v204, s11, v168
	v_cndmask_b32_e32 v241, v177, v131, vcc
	v_cndmask_b32_e32 v240, v176, v160, vcc
	ds_read_b128 v[176:179], v188
	ds_read_b128 v[180:183], v188 offset:1024
	ds_read_b128 v[184:187], v188 offset:2048
	ds_read_b128 v[188:191], v188 offset:3072
	ds_read_b128 v[192:195], v204
	ds_read_b128 v[196:199], v204 offset:1024
	ds_read_b128 v[200:203], v204 offset:2048
	ds_read_b128 v[204:207], v204 offset:3072
	v_cndmask_b32_e32 v243, v165, v161, vcc
	v_cndmask_b32_e32 v242, v164, v162, vcc
	v_lshl_add_u64 v[244:245], v[166:167], 0, v[154:155]
	s_add_i32 m0, s15, 0xc000
	ds_read_b128 v[208:211], v175
	ds_read_b128 v[212:215], v175 offset:1024
	ds_read_b128 v[216:219], v175 offset:2048
	ds_read_b128 v[220:223], v175 offset:3072
	ds_read_b128 v[224:227], v175 offset:4096
	ds_read_b128 v[228:231], v175 offset:5120
	ds_read_b128 v[232:235], v175 offset:6144
	ds_read_b128 v[236:239], v175 offset:7168
	global_load_lds_dwordx4 v[244:245], off
	v_lshl_add_u64 v[244:245], v[166:167], 0, v[152:153]
	s_add_i32 m0, s15, 0xe000
	s_nop 0
	global_load_lds_dwordx4 v[244:245], off
	s_setprio 0
	s_waitcnt vmcnt(8) lgkmcnt(0)
	s_barrier
	v_mfma_f32_16x16x32_bf16 v[124:127], v[176:179], v[208:211], v[124:127]
	v_mfma_f32_16x16x32_bf16 v[116:119], v[184:187], v[208:211], v[116:119]
	v_mfma_f32_16x16x32_bf16 v[108:111], v[176:179], v[216:219], v[108:111]
	v_mfma_f32_16x16x32_bf16 v[100:103], v[184:187], v[216:219], v[100:103]
	v_mfma_f32_16x16x32_bf16 v[92:95], v[176:179], v[224:227], v[92:95]
	v_mfma_f32_16x16x32_bf16 v[84:87], v[184:187], v[224:227], v[84:87]
	v_mfma_f32_16x16x32_bf16 v[76:79], v[176:179], v[232:235], v[76:79]
	v_mfma_f32_16x16x32_bf16 v[68:71], v[184:187], v[232:235], v[68:71]
	v_mfma_f32_16x16x32_bf16 v[124:127], v[180:183], v[212:215], v[124:127]
	v_mfma_f32_16x16x32_bf16 v[116:119], v[188:191], v[212:215], v[116:119]
	v_mfma_f32_16x16x32_bf16 v[108:111], v[180:183], v[220:223], v[108:111]
	v_mfma_f32_16x16x32_bf16 v[100:103], v[188:191], v[220:223], v[100:103]
	v_mfma_f32_16x16x32_bf16 v[92:95], v[180:183], v[228:231], v[92:95]
	v_mfma_f32_16x16x32_bf16 v[84:87], v[188:191], v[228:231], v[84:87]
	v_mfma_f32_16x16x32_bf16 v[76:79], v[180:183], v[236:239], v[76:79]
	v_mfma_f32_16x16x32_bf16 v[68:71], v[188:191], v[236:239], v[68:71]
	v_mfma_f32_16x16x32_bf16 v[120:123], v[192:195], v[208:211], v[120:123]
	v_mfma_f32_16x16x32_bf16 v[112:115], v[200:203], v[208:211], v[112:115]
	v_mfma_f32_16x16x32_bf16 v[104:107], v[192:195], v[216:219], v[104:107]
	v_mfma_f32_16x16x32_bf16 v[96:99], v[200:203], v[216:219], v[96:99]
	v_mfma_f32_16x16x32_bf16 v[88:91], v[192:195], v[224:227], v[88:91]
	v_mfma_f32_16x16x32_bf16 v[80:83], v[200:203], v[224:227], v[80:83]
	v_mfma_f32_16x16x32_bf16 v[72:75], v[192:195], v[232:235], v[72:75]
	v_mfma_f32_16x16x32_bf16 v[64:67], v[200:203], v[232:235], v[64:67]
	v_mfma_f32_16x16x32_bf16 v[120:123], v[196:199], v[212:215], v[120:123]
	v_mfma_f32_16x16x32_bf16 v[112:115], v[204:207], v[212:215], v[112:115]
	v_mfma_f32_16x16x32_bf16 v[104:107], v[196:199], v[220:223], v[104:107]
	v_mfma_f32_16x16x32_bf16 v[96:99], v[204:207], v[220:223], v[96:99]
	v_mfma_f32_16x16x32_bf16 v[88:91], v[196:199], v[228:231], v[88:91]
	v_mfma_f32_16x16x32_bf16 v[80:83], v[204:207], v[228:231], v[80:83]
	v_mfma_f32_16x16x32_bf16 v[72:75], v[196:199], v[236:239], v[72:75]
	v_mfma_f32_16x16x32_bf16 v[64:67], v[204:207], v[236:239], v[64:67]
	s_barrier
	s_add_i32 s3, s3, s14
	v_lshl_add_u64 v[244:245], v[242:243], 0, v[128:129]
	s_mov_b32 m0, s3
	ds_read_b128 v[208:211], v175 offset:16384
	ds_read_b128 v[212:215], v175 offset:17408
	ds_read_b128 v[216:219], v175 offset:18432
	ds_read_b128 v[220:223], v175 offset:19456
	ds_read_b128 v[224:227], v175 offset:20480
	ds_read_b128 v[228:231], v175 offset:21504
	ds_read_b128 v[232:235], v175 offset:22528
	ds_read_b128 v[236:239], v175 offset:23552
	global_load_lds_dwordx4 v[244:245], off
	v_lshl_add_u64 v[246:247], v[242:243], 0, v[144:145]
	s_add_i32 m0, s3, 0x2000
	v_lshl_add_u64 v[248:249], v[242:243], 0, s[98:99]
	s_add_i32 s3, s11, s14
	global_load_lds_dwordx4 v[246:247], off
	v_lshl_add_u64 v[250:251], v[248:249], 0, v[128:129]
	s_mov_b32 m0, s3
	v_lshl_add_u64 v[248:249], v[248:249], 0, v[144:145]
	global_load_lds_dwordx4 v[250:251], off
	s_add_i32 m0, s3, 0x2000
	v_lshl_add_u64 v[250:251], v[240:241], 0, v[146:147]
	global_load_lds_dwordx4 v[248:249], off
	v_lshl_add_u64 v[248:249], v[240:241], 0, v[148:149]
	s_mov_b32 m0, s15
	s_nop 0
	global_load_lds_dwordx4 v[248:249], off
	s_mov_b32 m0, s16
	s_nop 0
	global_load_lds_dwordx4 v[250:251], off
	s_waitcnt vmcnt(8) lgkmcnt(0)
	s_barrier
; #define PG8_STAGE(bufoff, gbase, voff) do { _Pragma("unroll") for (int _i = 0; _i < 2; ++_i) \
;         __builtin_amdgcn_global_load_lds((const unsigned*)((const char*)(gbase) + (voff)[_i]), (PG8_LAS unsigned*)(lds + (bufoff) + ldsw + _i * 8192), 16, 0, 0); } while (0)
; #define PG8_LDA(dst, b, h) do { _Pragma("unroll") for (int m = 0; m < 4; ++m) _Pragma("unroll") for (int k = 0; k < 2; ++k) dst[m][k] = *(const PG8_LAS bf16x8*)(lds + PG8_SA(b, h) + aoff + m * 2048 + k * 1024); } while (0)
; #define PG8_LDB(dst, b, h) do { _Pragma("unroll") for (int n = 0; n < 2; ++n) _Pragma("unroll") for (int k = 0; k < 2; ++k) dst[n][k] = *(const PG8_LAS bf16x8*)(lds + PG8_SB(b, h) + boff + n * 2048 + k * 1024); } while (0)
; #define PG8_MMA(ai, bj, At, Bt) do { __builtin_amdgcn_s_setprio(1); _Pragma("unroll") for (int m = 0; m < 4; ++m) _Pragma("unroll") for (int n = 0; n < 2; ++n) _Pragma("unroll") for (int k = 0; k < 2; ++k) \
;         acc[ai][bj][m][n] = __builtin_amdgcn_mfma_f32_16x16x32_bf16(Bt[n][k], At[m][k], acc[ai][bj][m][n], 0, 0, 0); __builtin_amdgcn_s_setprio(0); } while (0)
; #define PG8_WAIT_V(n) asm volatile("s_waitcnt vmcnt(" #n ")" ::: "memory")
; #define PG8_WAIT_L(n) asm volatile("s_waitcnt lgkmcnt(" #n ")" ::: "memory")
; #define PG8_BAR __builtin_amdgcn_s_barrier()
; #define PG8_SCHED __builtin_amdgcn_sched_barrier(0)
; template <class Epi, class Sched, bool ALIGN_EPI = false, bool SP2 = false>
; __device__ __forceinline__ void gemm_phase(PG8_LAS unsigned char* lds, const Gemm g, const Sched& S, const Epi& E, int tid_in) {
;     ...
;             PG8_WAIT_V(8); PG8_WAIT_L(0); PG8_BAR; PG8_MMA(1, 0, At, B0); PG8_MMA(1, 1, At, B1); PG8_BAR; PG8_SCHED;
;             PG8_LDB(B0, 1, 0); PG8_LDB(B1, 1, 1); PG8_SCHED; PG8_LDA(At, 1, 0); PG8_STAGE(PG8_SA(0, 1), a2 + hstep, voffA);
;             PG8_WAIT_V(8); PG8_WAIT_L(0); PG8_BAR; PG8_MMA(0, 0, At, B0); PG8_MMA(0, 1, At, B1); PG8_BAR; PG8_SCHED;
	v_mfma_f32_16x16x32_bf16 v[60:63], v[176:179], v[208:211], v[60:63]
	v_mfma_f32_16x16x32_bf16 v[52:55], v[184:187], v[208:211], v[52:55]
	v_mfma_f32_16x16x32_bf16 v[44:47], v[176:179], v[216:219], v[44:47]
	v_mfma_f32_16x16x32_bf16 v[36:39], v[184:187], v[216:219], v[36:39]
	v_mfma_f32_16x16x32_bf16 v[28:31], v[176:179], v[224:227], v[28:31]
	v_mfma_f32_16x16x32_bf16 v[20:23], v[184:187], v[224:227], v[20:23]
	v_mfma_f32_16x16x32_bf16 v[12:15], v[176:179], v[232:235], v[12:15]
	v_mfma_f32_16x16x32_bf16 v[4:7], v[184:187], v[232:235], v[4:7]
	v_mfma_f32_16x16x32_bf16 v[60:63], v[180:183], v[212:215], v[60:63]
	v_mfma_f32_16x16x32_bf16 v[52:55], v[188:191], v[212:215], v[52:55]
	v_mfma_f32_16x16x32_bf16 v[44:47], v[180:183], v[220:223], v[44:47]
	v_mfma_f32_16x16x32_bf16 v[36:39], v[188:191], v[220:223], v[36:39]
	v_mfma_f32_16x16x32_bf16 v[28:31], v[180:183], v[228:231], v[28:31]
	v_mfma_f32_16x16x32_bf16 v[20:23], v[188:191], v[228:231], v[20:23]
	v_mfma_f32_16x16x32_bf16 v[12:15], v[180:183], v[236:239], v[12:15]
	v_mfma_f32_16x16x32_bf16 v[4:7], v[188:191], v[236:239], v[4:7]
	v_mfma_f32_16x16x32_bf16 v[56:59], v[192:195], v[208:211], v[56:59]
	v_mfma_f32_16x16x32_bf16 v[48:51], v[200:203], v[208:211], v[48:51]
	v_mfma_f32_16x16x32_bf16 v[40:43], v[192:195], v[216:219], v[40:43]
	v_mfma_f32_16x16x32_bf16 v[32:35], v[200:203], v[216:219], v[32:35]
	v_mfma_f32_16x16x32_bf16 v[24:27], v[192:195], v[224:227], v[24:27]
	v_mfma_f32_16x16x32_bf16 v[16:19], v[200:203], v[224:227], v[16:19]
	v_mfma_f32_16x16x32_bf16 v[8:11], v[192:195], v[232:235], v[8:11]
	v_mfma_f32_16x16x32_bf16 v[0:3], v[200:203], v[232:235], v[0:3]
	v_mfma_f32_16x16x32_bf16 v[56:59], v[196:199], v[212:215], v[56:59]
	v_mfma_f32_16x16x32_bf16 v[48:51], v[204:207], v[212:215], v[48:51]
	v_mfma_f32_16x16x32_bf16 v[40:43], v[196:199], v[220:223], v[40:43]
	v_mfma_f32_16x16x32_bf16 v[32:35], v[204:207], v[220:223], v[32:35]
	v_mfma_f32_16x16x32_bf16 v[24:27], v[196:199], v[228:231], v[24:27]
	v_mfma_f32_16x16x32_bf16 v[16:19], v[204:207], v[228:231], v[16:19]
	v_mfma_f32_16x16x32_bf16 v[8:11], v[196:199], v[236:239], v[8:11]
	v_mfma_f32_16x16x32_bf16 v[0:3], v[204:207], v[236:239], v[0:3]
	s_barrier
	s_setprio 1
	s_add_i32 s3, 0, 0x18000
	s_add_i32 s11, 0, 0x1c000
	v_add_u32_e32 v188, s3, v168
	v_add_u32_e32 v204, s11, v168
	ds_read_b128 v[176:179], v188
	ds_read_b128 v[180:183], v188 offset:1024
	ds_read_b128 v[184:187], v188 offset:2048
	ds_read_b128 v[188:191], v188 offset:3072
	ds_read_b128 v[192:195], v204
	ds_read_b128 v[196:199], v204 offset:1024
	ds_read_b128 v[200:203], v204 offset:2048
	ds_read_b128 v[204:207], v204 offset:3072
	v_lshl_add_u64 v[240:241], v[240:241], 0, s[98:99]
	s_mov_b32 m0, s17
	v_lshl_add_u64 v[252:253], v[240:241], 0, v[148:149]
	ds_read_b128 v[208:211], v175 offset:32768
	ds_read_b128 v[212:215], v175 offset:33792
	ds_read_b128 v[216:219], v175 offset:34816
	ds_read_b128 v[220:223], v175 offset:35840
	ds_read_b128 v[224:227], v175 offset:36864
	ds_read_b128 v[228:231], v175 offset:37888
	ds_read_b128 v[232:235], v175 offset:38912
	ds_read_b128 v[236:239], v175 offset:39936
	global_load_lds_dwordx4 v[252:253], off
	v_lshl_add_u64 v[240:241], v[240:241], 0, v[146:147]
	s_mov_b32 m0, s18
	s_nop 0
	global_load_lds_dwordx4 v[240:241], off
	s_setprio 0
	s_waitcnt vmcnt(8) lgkmcnt(0)
	s_barrier
	v_mfma_f32_16x16x32_bf16 v[124:127], v[176:179], v[208:211], v[124:127]
	v_mfma_f32_16x16x32_bf16 v[116:119], v[184:187], v[208:211], v[116:119]
	v_mfma_f32_16x16x32_bf16 v[108:111], v[176:179], v[216:219], v[108:111]
	v_mfma_f32_16x16x32_bf16 v[100:103], v[184:187], v[216:219], v[100:103]
	v_mfma_f32_16x16x32_bf16 v[92:95], v[176:179], v[224:227], v[92:95]
	v_mfma_f32_16x16x32_bf16 v[84:87], v[184:187], v[224:227], v[84:87]
	v_mfma_f32_16x16x32_bf16 v[76:79], v[176:179], v[232:235], v[76:79]
	v_mfma_f32_16x16x32_bf16 v[68:71], v[184:187], v[232:235], v[68:71]
	v_mfma_f32_16x16x32_bf16 v[124:127], v[180:183], v[212:215], v[124:127]
	v_mfma_f32_16x16x32_bf16 v[116:119], v[188:191], v[212:215], v[116:119]
	v_mfma_f32_16x16x32_bf16 v[108:111], v[180:183], v[220:223], v[108:111]
	v_mfma_f32_16x16x32_bf16 v[100:103], v[188:191], v[220:223], v[100:103]
	v_mfma_f32_16x16x32_bf16 v[92:95], v[180:183], v[228:231], v[92:95]
	v_mfma_f32_16x16x32_bf16 v[84:87], v[188:191], v[228:231], v[84:87]
	v_mfma_f32_16x16x32_bf16 v[76:79], v[180:183], v[236:239], v[76:79]
	v_mfma_f32_16x16x32_bf16 v[68:71], v[188:191], v[236:239], v[68:71]
	v_mfma_f32_16x16x32_bf16 v[120:123], v[192:195], v[208:211], v[120:123]
	v_mfma_f32_16x16x32_bf16 v[112:115], v[200:203], v[208:211], v[112:115]
	v_mfma_f32_16x16x32_bf16 v[104:107], v[192:195], v[216:219], v[104:107]
	v_mfma_f32_16x16x32_bf16 v[96:99], v[200:203], v[216:219], v[96:99]
	v_mfma_f32_16x16x32_bf16 v[88:91], v[192:195], v[224:227], v[88:91]
	v_mfma_f32_16x16x32_bf16 v[80:83], v[200:203], v[224:227], v[80:83]
	v_mfma_f32_16x16x32_bf16 v[72:75], v[192:195], v[232:235], v[72:75]
	v_mfma_f32_16x16x32_bf16 v[64:67], v[200:203], v[232:235], v[64:67]
	v_mfma_f32_16x16x32_bf16 v[120:123], v[196:199], v[212:215], v[120:123]
	v_mfma_f32_16x16x32_bf16 v[112:115], v[204:207], v[212:215], v[112:115]
	v_mfma_f32_16x16x32_bf16 v[104:107], v[196:199], v[220:223], v[104:107]
	v_mfma_f32_16x16x32_bf16 v[96:99], v[204:207], v[220:223], v[96:99]
	v_mfma_f32_16x16x32_bf16 v[88:91], v[196:199], v[228:231], v[88:91]
	v_mfma_f32_16x16x32_bf16 v[80:83], v[204:207], v[228:231], v[80:83]
	v_mfma_f32_16x16x32_bf16 v[72:75], v[196:199], v[236:239], v[72:75]
	v_mfma_f32_16x16x32_bf16 v[64:67], v[204:207], v[236:239], v[64:67]
	s_barrier
; #define PG8_STAGE(bufoff, gbase, voff) do { _Pragma("unroll") for (int _i = 0; _i < 2; ++_i) \
;         __builtin_amdgcn_global_load_lds((const unsigned*)((const char*)(gbase) + (voff)[_i]), (PG8_LAS unsigned*)(lds + (bufoff) + ldsw + _i * 8192), 16, 0, 0); } while (0)
; #define PG8_LDA(dst, b, h) do { _Pragma("unroll") for (int m = 0; m < 4; ++m) _Pragma("unroll") for (int k = 0; k < 2; ++k) dst[m][k] = *(const PG8_LAS bf16x8*)(lds + PG8_SA(b, h) + aoff + m * 2048 + k * 1024); } while (0)
; #define PG8_MMA(ai, bj, At, Bt) do { __builtin_amdgcn_s_setprio(1); _Pragma("unroll") for (int m = 0; m < 4; ++m) _Pragma("unroll") for (int n = 0; n < 2; ++n) _Pragma("unroll") for (int k = 0; k < 2; ++k) \
;         acc[ai][bj][m][n] = __builtin_amdgcn_mfma_f32_16x16x32_bf16(Bt[n][k], At[m][k], acc[ai][bj][m][n], 0, 0, 0); __builtin_amdgcn_s_setprio(0); } while (0)
; #define PG8_WAIT_V(n) asm volatile("s_waitcnt vmcnt(" #n ")" ::: "memory")
; #define PG8_WAIT_L(n) asm volatile("s_waitcnt lgkmcnt(" #n ")" ::: "memory")
; #define PG8_BAR __builtin_amdgcn_s_barrier()
; #define PG8_SCHED __builtin_amdgcn_sched_barrier(0)
; template <class Epi, class Sched, bool ALIGN_EPI = false, bool SP2 = false>
; __device__ __forceinline__ void gemm_phase(PG8_LAS unsigned char* lds, const Gemm g, const Sched& S, const Epi& E, int tid_in) {
;     ...
;         for (int t = 0; t < nt; t += 2) {
;             const bool last = (t == nt - 2);
;             const char* a1 = cA + (size_t)(t + 1) * kstep;
;             const char* a2 = last ? nA : cA + (size_t)(t + 2) * kstep; const char* b2 = last ? nB : cB + (size_t)(t + 2) * kstep;
;             const char* a3 = a2 + kstep; const char* b3 = b2 + kstep;
;     ...
;             PG8_LDA(At, 1, 1); PG8_STAGE(PG8_SB(1, 0), b3, voffB); PG8_STAGE(PG8_SB(1, 1), b3 + hstep, voffB); PG8_STAGE(PG8_SA(1, 0), a3, voffA);
;             PG8_WAIT_V(8); PG8_WAIT_L(0); PG8_BAR; PG8_MMA(1, 0, At, B0); PG8_MMA(1, 1, At, B1); PG8_BAR; PG8_SCHED;
	s_add_i32 s3, s3, s14
	v_lshl_add_u64 v[240:241], v[244:245], 0, s[70:71]
	s_mov_b32 m0, s3
	ds_read_b128 v[208:211], v175 offset:49152
	ds_read_b128 v[212:215], v175 offset:50176
	ds_read_b128 v[216:219], v175 offset:51200
	ds_read_b128 v[220:223], v175 offset:52224
	ds_read_b128 v[224:227], v175 offset:53248
	ds_read_b128 v[228:231], v175 offset:54272
	ds_read_b128 v[232:235], v175 offset:55296
	ds_read_b128 v[236:239], v175 offset:56320
	global_load_lds_dwordx4 v[240:241], off
	v_lshl_add_u64 v[240:241], v[246:247], 0, s[70:71]
	s_add_i32 m0, s3, 0x2000
	s_add_i32 s3, s11, s14
	global_load_lds_dwordx4 v[240:241], off
	v_lshl_add_u64 v[240:241], v[242:243], 0, s[86:87]
	v_lshl_add_u64 v[242:243], v[240:241], 0, v[128:129]
	s_mov_b32 m0, s3
	v_lshl_add_u64 v[240:241], v[240:241], 0, v[144:145]
	global_load_lds_dwordx4 v[242:243], off
	s_add_i32 m0, s3, 0x2000
	s_nop 0
	global_load_lds_dwordx4 v[240:241], off
	v_lshl_add_u64 v[240:241], v[248:249], 0, s[70:71]
	s_mov_b32 m0, s19
	s_nop 0
	global_load_lds_dwordx4 v[240:241], off
	v_lshl_add_u64 v[240:241], v[250:251], 0, s[70:71]
	s_mov_b32 m0, s1
	s_nop 0
	global_load_lds_dwordx4 v[240:241], off
	s_waitcnt vmcnt(8) lgkmcnt(0)
	s_barrier
	v_mfma_f32_16x16x32_bf16 v[60:63], v[176:179], v[208:211], v[60:63]
	v_mfma_f32_16x16x32_bf16 v[52:55], v[184:187], v[208:211], v[52:55]
	v_mfma_f32_16x16x32_bf16 v[44:47], v[176:179], v[216:219], v[44:47]
	v_mfma_f32_16x16x32_bf16 v[36:39], v[184:187], v[216:219], v[36:39]
	v_mfma_f32_16x16x32_bf16 v[28:31], v[176:179], v[224:227], v[28:31]
	v_mfma_f32_16x16x32_bf16 v[20:23], v[184:187], v[224:227], v[20:23]
	v_mfma_f32_16x16x32_bf16 v[12:15], v[176:179], v[232:235], v[12:15]
	v_mfma_f32_16x16x32_bf16 v[4:7], v[184:187], v[232:235], v[4:7]
	v_mfma_f32_16x16x32_bf16 v[60:63], v[180:183], v[212:215], v[60:63]
	v_mfma_f32_16x16x32_bf16 v[52:55], v[188:191], v[212:215], v[52:55]
	v_mfma_f32_16x16x32_bf16 v[44:47], v[180:183], v[220:223], v[44:47]
	v_mfma_f32_16x16x32_bf16 v[36:39], v[188:191], v[220:223], v[36:39]
	v_mfma_f32_16x16x32_bf16 v[28:31], v[180:183], v[228:231], v[28:31]
	v_mfma_f32_16x16x32_bf16 v[20:23], v[188:191], v[228:231], v[20:23]
	v_mfma_f32_16x16x32_bf16 v[12:15], v[180:183], v[236:239], v[12:15]
	v_mfma_f32_16x16x32_bf16 v[4:7], v[188:191], v[236:239], v[4:7]
	v_mfma_f32_16x16x32_bf16 v[56:59], v[192:195], v[208:211], v[56:59]
	v_mfma_f32_16x16x32_bf16 v[48:51], v[200:203], v[208:211], v[48:51]
	v_mfma_f32_16x16x32_bf16 v[40:43], v[192:195], v[216:219], v[40:43]
	v_mfma_f32_16x16x32_bf16 v[32:35], v[200:203], v[216:219], v[32:35]
	v_mfma_f32_16x16x32_bf16 v[24:27], v[192:195], v[224:227], v[24:27]
	v_mfma_f32_16x16x32_bf16 v[16:19], v[200:203], v[224:227], v[16:19]
	v_mfma_f32_16x16x32_bf16 v[8:11], v[192:195], v[232:235], v[8:11]
	v_mfma_f32_16x16x32_bf16 v[0:3], v[200:203], v[232:235], v[0:3]
	v_mfma_f32_16x16x32_bf16 v[56:59], v[196:199], v[212:215], v[56:59]
	v_mfma_f32_16x16x32_bf16 v[48:51], v[204:207], v[212:215], v[48:51]
	v_mfma_f32_16x16x32_bf16 v[40:43], v[196:199], v[220:223], v[40:43]
	v_mfma_f32_16x16x32_bf16 v[32:35], v[204:207], v[220:223], v[32:35]
	v_mfma_f32_16x16x32_bf16 v[24:27], v[196:199], v[228:231], v[24:27]
	v_mfma_f32_16x16x32_bf16 v[16:19], v[204:207], v[228:231], v[16:19]
	v_mfma_f32_16x16x32_bf16 v[8:11], v[196:199], v[236:239], v[8:11]
	v_mfma_f32_16x16x32_bf16 v[0:3], v[204:207], v[236:239], v[0:3]
	s_barrier
	s_setprio 1
	s_add_i32 s2, s2, 2
	v_lshl_add_u64 v[164:165], v[164:165], 0, s[82:83]
	s_cmp_gt_u32 s2, 29
	v_lshl_add_u64 v[166:167], v[166:167], 0, s[82:83]
	s_cbranch_scc0 .LBB0_588
	s_setprio 0
	s_and_b64 vcc, exec, s[8:9]
	s_cbranch_vccz .LBB0_591
	s_barrier

; #define PG8_STAGE(bufoff, gbase, voff) do { _Pragma("unroll") for (int _i = 0; _i < 2; ++_i) \
;         __builtin_amdgcn_global_load_lds((const unsigned*)((const char*)(gbase) + (voff)[_i]), (PG8_LAS unsigned*)(lds + (bufoff) + ldsw + _i * 8192), 16, 0, 0); } while (0)
; #define PG8_LDA(dst, b, h) do { _Pragma("unroll") for (int m = 0; m < 4; ++m) _Pragma("unroll") for (int k = 0; k < 2; ++k) dst[m][k] = *(const PG8_LAS bf16x8*)(lds + PG8_SA(b, h) + aoff + m * 2048 + k * 1024); } while (0)
; #define PG8_LDB(dst, b, h) do { _Pragma("unroll") for (int n = 0; n < 2; ++n) _Pragma("unroll") for (int k = 0; k < 2; ++k) dst[n][k] = *(const PG8_LAS bf16x8*)(lds + PG8_SB(b, h) + boff + n * 2048 + k * 1024); } while (0)
; #define PG8_MMA(ai, bj, At, Bt) do { __builtin_amdgcn_s_setprio(1); _Pragma("unroll") for (int m = 0; m < 4; ++m) _Pragma("unroll") for (int n = 0; n < 2; ++n) _Pragma("unroll") for (int k = 0; k < 2; ++k) \
;         acc[ai][bj][m][n] = __builtin_amdgcn_mfma_f32_16x16x32_bf16(Bt[n][k], At[m][k], acc[ai][bj][m][n], 0, 0, 0); __builtin_amdgcn_s_setprio(0); } while (0)
; #define PG8_WAIT_V(n) asm volatile("s_waitcnt vmcnt(" #n ")" ::: "memory")
; #define PG8_WAIT_L(n) asm volatile("s_waitcnt lgkmcnt(" #n ")" ::: "memory")
; #define PG8_BAR __builtin_amdgcn_s_barrier()
; #define PG8_SCHED __builtin_amdgcn_sched_barrier(0)
; template <class Epi, class Sched, bool ALIGN_EPI = false, bool SP2 = false>
; __device__ __forceinline__ void gemm_phase(PG8_LAS unsigned char* lds, const Gemm g, const Sched& S, const Epi& E, int tid_in) {
;     ...
;             PG8_LDB(B0, 0, 0); PG8_LDB(B1, 0, 1); PG8_SCHED; PG8_LDA(At, 0, 0); PG8_STAGE(PG8_SA(1, 1), a1 + hstep, voffA);
;             PG8_WAIT_V(8); PG8_WAIT_L(0); PG8_BAR; PG8_MMA(0, 0, At, B0); PG8_MMA(0, 1, At, B1); PG8_BAR; PG8_SCHED;
;             PG8_LDA(At, 0, 1); PG8_STAGE(PG8_SB(0, 0), b2, voffB); PG8_STAGE(PG8_SB(0, 1), b2 + hstep, voffB); PG8_STAGE(PG8_SA(0, 0), a2, voffA);
;             PG8_WAIT_V(8); PG8_WAIT_L(0); PG8_BAR; PG8_MMA(1, 0, At, B0); PG8_MMA(1, 1, At, B1); PG8_BAR; PG8_SCHED;
.LBB0_683:
	s_cmpk_eq_i32 s2, 0x54
	s_cselect_b64 vcc, -1, 0
	s_add_i32 s3, 0, 0x10000
	v_add_u32_e32 v169, s3, v166
	s_add_i32 s8, 0, 0x14000
	ds_read_b128 v[176:179], v169
	ds_read_b128 v[180:183], v169 offset:1024
	ds_read_b128 v[184:187], v169 offset:2048
	ds_read_b128 v[188:191], v169 offset:3072
	v_add_u32_e32 v169, s8, v166
	ds_read_b128 v[192:195], v169
	ds_read_b128 v[196:199], v169 offset:1024
	ds_read_b128 v[200:203], v169 offset:2048
	ds_read_b128 v[204:207], v169 offset:3072
	v_lshl_add_u64 v[164:165], v[162:163], 0, s[82:83]
	v_cndmask_b32_e32 v241, v165, v157, vcc
	v_cndmask_b32_e32 v240, v164, v156, vcc
	v_cndmask_b32_e32 v243, v161, v159, vcc
	v_cndmask_b32_e32 v242, v160, v158, vcc
	v_lshl_add_u64 v[244:245], v[162:163], 0, v[154:155]
	s_add_i32 m0, s14, 0xc000
	ds_read_b128 v[208:211], v168
	ds_read_b128 v[212:215], v168 offset:1024
	ds_read_b128 v[216:219], v168 offset:2048
	ds_read_b128 v[220:223], v168 offset:3072
	ds_read_b128 v[224:227], v168 offset:4096
	ds_read_b128 v[228:231], v168 offset:5120
	ds_read_b128 v[232:235], v168 offset:6144
	ds_read_b128 v[236:239], v168 offset:7168
	global_load_lds_dwordx4 v[244:245], off
	v_lshl_add_u64 v[162:163], v[162:163], 0, v[152:153]
	s_add_i32 m0, s14, 0xe000
	s_nop 0
	global_load_lds_dwordx4 v[162:163], off
	s_setprio 0
	s_waitcnt vmcnt(8) lgkmcnt(0)
	s_barrier
	v_mfma_f32_16x16x32_bf16 v[124:127], v[176:179], v[208:211], v[124:127]
	v_mfma_f32_16x16x32_bf16 v[120:123], v[184:187], v[208:211], v[120:123]
	v_mfma_f32_16x16x32_bf16 v[116:119], v[176:179], v[216:219], v[116:119]
	v_mfma_f32_16x16x32_bf16 v[108:111], v[184:187], v[216:219], v[108:111]
	v_mfma_f32_16x16x32_bf16 v[100:103], v[176:179], v[224:227], v[100:103]
	v_mfma_f32_16x16x32_bf16 v[92:95], v[184:187], v[224:227], v[92:95]
	v_mfma_f32_16x16x32_bf16 v[84:87], v[176:179], v[232:235], v[84:87]
	v_mfma_f32_16x16x32_bf16 v[76:79], v[184:187], v[232:235], v[76:79]
	v_mfma_f32_16x16x32_bf16 v[124:127], v[180:183], v[212:215], v[124:127]
	v_mfma_f32_16x16x32_bf16 v[120:123], v[188:191], v[212:215], v[120:123]
	v_mfma_f32_16x16x32_bf16 v[116:119], v[180:183], v[220:223], v[116:119]
	v_mfma_f32_16x16x32_bf16 v[108:111], v[188:191], v[220:223], v[108:111]
	v_mfma_f32_16x16x32_bf16 v[100:103], v[180:183], v[228:231], v[100:103]
	v_mfma_f32_16x16x32_bf16 v[92:95], v[188:191], v[228:231], v[92:95]
	v_mfma_f32_16x16x32_bf16 v[84:87], v[180:183], v[236:239], v[84:87]
	v_mfma_f32_16x16x32_bf16 v[76:79], v[188:191], v[236:239], v[76:79]
	v_mfma_f32_16x16x32_bf16 v[112:115], v[192:195], v[208:211], v[112:115]
	v_mfma_f32_16x16x32_bf16 v[104:107], v[200:203], v[208:211], v[104:107]
	v_mfma_f32_16x16x32_bf16 v[96:99], v[192:195], v[216:219], v[96:99]
	v_mfma_f32_16x16x32_bf16 v[88:91], v[200:203], v[216:219], v[88:91]
	v_mfma_f32_16x16x32_bf16 v[80:83], v[192:195], v[224:227], v[80:83]
	v_mfma_f32_16x16x32_bf16 v[72:75], v[200:203], v[224:227], v[72:75]
	v_mfma_f32_16x16x32_bf16 v[68:71], v[192:195], v[232:235], v[68:71]
	v_mfma_f32_16x16x32_bf16 v[64:67], v[200:203], v[232:235], v[64:67]
	v_mfma_f32_16x16x32_bf16 v[112:115], v[196:199], v[212:215], v[112:115]
	v_mfma_f32_16x16x32_bf16 v[104:107], v[204:207], v[212:215], v[104:107]
	v_mfma_f32_16x16x32_bf16 v[96:99], v[196:199], v[220:223], v[96:99]
	v_mfma_f32_16x16x32_bf16 v[88:91], v[204:207], v[220:223], v[88:91]
	v_mfma_f32_16x16x32_bf16 v[80:83], v[196:199], v[228:231], v[80:83]
	v_mfma_f32_16x16x32_bf16 v[72:75], v[204:207], v[228:231], v[72:75]
	v_mfma_f32_16x16x32_bf16 v[68:71], v[196:199], v[236:239], v[68:71]
	v_mfma_f32_16x16x32_bf16 v[64:67], v[204:207], v[236:239], v[64:67]
	s_barrier
	s_add_i32 s3, s3, s1
	v_lshl_add_u64 v[162:163], v[242:243], 0, v[128:129]
	s_mov_b32 m0, s3
	ds_read_b128 v[208:211], v168 offset:16384
	ds_read_b128 v[212:215], v168 offset:17408
	ds_read_b128 v[216:219], v168 offset:18432
	ds_read_b128 v[220:223], v168 offset:19456
	ds_read_b128 v[224:227], v168 offset:20480
	ds_read_b128 v[228:231], v168 offset:21504
	ds_read_b128 v[232:235], v168 offset:22528
	ds_read_b128 v[236:239], v168 offset:23552
	global_load_lds_dwordx4 v[162:163], off
	v_lshl_add_u64 v[244:245], v[242:243], 0, v[144:145]
	s_add_i32 m0, s3, 0x2000
	v_lshl_add_u64 v[246:247], v[242:243], 0, s[74:75]
	s_add_i32 s3, s8, s1
	global_load_lds_dwordx4 v[244:245], off
	v_lshl_add_u64 v[248:249], v[246:247], 0, v[128:129]
	s_mov_b32 m0, s3
	v_lshl_add_u64 v[246:247], v[246:247], 0, v[144:145]
	global_load_lds_dwordx4 v[248:249], off
	s_add_i32 m0, s3, 0x2000
	v_lshl_add_u64 v[248:249], v[240:241], 0, v[146:147]
	global_load_lds_dwordx4 v[246:247], off
	v_lshl_add_u64 v[246:247], v[240:241], 0, v[148:149]
	s_mov_b32 m0, s14
	s_nop 0
	global_load_lds_dwordx4 v[246:247], off
	s_mov_b32 m0, s15
	s_nop 0
	global_load_lds_dwordx4 v[248:249], off
	s_waitcnt vmcnt(8) lgkmcnt(0)
	s_barrier
; #define PG8_STAGE(bufoff, gbase, voff) do { _Pragma("unroll") for (int _i = 0; _i < 2; ++_i) \
;         __builtin_amdgcn_global_load_lds((const unsigned*)((const char*)(gbase) + (voff)[_i]), (PG8_LAS unsigned*)(lds + (bufoff) + ldsw + _i * 8192), 16, 0, 0); } while (0)
; #define PG8_LDA(dst, b, h) do { _Pragma("unroll") for (int m = 0; m < 4; ++m) _Pragma("unroll") for (int k = 0; k < 2; ++k) dst[m][k] = *(const PG8_LAS bf16x8*)(lds + PG8_SA(b, h) + aoff + m * 2048 + k * 1024); } while (0)
; #define PG8_LDB(dst, b, h) do { _Pragma("unroll") for (int n = 0; n < 2; ++n) _Pragma("unroll") for (int k = 0; k < 2; ++k) dst[n][k] = *(const PG8_LAS bf16x8*)(lds + PG8_SB(b, h) + boff + n * 2048 + k * 1024); } while (0)
; #define PG8_MMA(ai, bj, At, Bt) do { __builtin_amdgcn_s_setprio(1); _Pragma("unroll") for (int m = 0; m < 4; ++m) _Pragma("unroll") for (int n = 0; n < 2; ++n) _Pragma("unroll") for (int k = 0; k < 2; ++k) \
;         acc[ai][bj][m][n] = __builtin_amdgcn_mfma_f32_16x16x32_bf16(Bt[n][k], At[m][k], acc[ai][bj][m][n], 0, 0, 0); __builtin_amdgcn_s_setprio(0); } while (0)
; #define PG8_WAIT_V(n) asm volatile("s_waitcnt vmcnt(" #n ")" ::: "memory")
; #define PG8_WAIT_L(n) asm volatile("s_waitcnt lgkmcnt(" #n ")" ::: "memory")
; #define PG8_BAR __builtin_amdgcn_s_barrier()
; #define PG8_SCHED __builtin_amdgcn_sched_barrier(0)
; template <class Epi, class Sched, bool ALIGN_EPI = false, bool SP2 = false>
; __device__ __forceinline__ void gemm_phase(PG8_LAS unsigned char* lds, const Gemm g, const Sched& S, const Epi& E, int tid_in) {
;     ...
;             PG8_WAIT_V(8); PG8_WAIT_L(0); PG8_BAR; PG8_MMA(1, 0, At, B0); PG8_MMA(1, 1, At, B1); PG8_BAR; PG8_SCHED;
;             PG8_LDB(B0, 1, 0); PG8_LDB(B1, 1, 1); PG8_SCHED; PG8_LDA(At, 1, 0); PG8_STAGE(PG8_SA(0, 1), a2 + hstep, voffA);
;             PG8_WAIT_V(8); PG8_WAIT_L(0); PG8_BAR; PG8_MMA(0, 0, At, B0); PG8_MMA(0, 1, At, B1); PG8_BAR; PG8_SCHED;
	v_mfma_f32_16x16x32_bf16 v[60:63], v[176:179], v[208:211], v[60:63]
	v_mfma_f32_16x16x32_bf16 v[56:59], v[184:187], v[208:211], v[56:59]
	v_mfma_f32_16x16x32_bf16 v[52:55], v[176:179], v[216:219], v[52:55]
	v_mfma_f32_16x16x32_bf16 v[44:47], v[184:187], v[216:219], v[44:47]
	v_mfma_f32_16x16x32_bf16 v[36:39], v[176:179], v[224:227], v[36:39]
	v_mfma_f32_16x16x32_bf16 v[28:31], v[184:187], v[224:227], v[28:31]
	v_mfma_f32_16x16x32_bf16 v[20:23], v[176:179], v[232:235], v[20:23]
	v_mfma_f32_16x16x32_bf16 v[12:15], v[184:187], v[232:235], v[12:15]
	v_mfma_f32_16x16x32_bf16 v[60:63], v[180:183], v[212:215], v[60:63]
	v_mfma_f32_16x16x32_bf16 v[56:59], v[188:191], v[212:215], v[56:59]
	v_mfma_f32_16x16x32_bf16 v[52:55], v[180:183], v[220:223], v[52:55]
	v_mfma_f32_16x16x32_bf16 v[44:47], v[188:191], v[220:223], v[44:47]
	v_mfma_f32_16x16x32_bf16 v[36:39], v[180:183], v[228:231], v[36:39]
	v_mfma_f32_16x16x32_bf16 v[28:31], v[188:191], v[228:231], v[28:31]
	v_mfma_f32_16x16x32_bf16 v[20:23], v[180:183], v[236:239], v[20:23]
	v_mfma_f32_16x16x32_bf16 v[12:15], v[188:191], v[236:239], v[12:15]
	v_mfma_f32_16x16x32_bf16 v[48:51], v[192:195], v[208:211], v[48:51]
	v_mfma_f32_16x16x32_bf16 v[40:43], v[200:203], v[208:211], v[40:43]
	v_mfma_f32_16x16x32_bf16 v[32:35], v[192:195], v[216:219], v[32:35]
	v_mfma_f32_16x16x32_bf16 v[24:27], v[200:203], v[216:219], v[24:27]
	v_mfma_f32_16x16x32_bf16 v[16:19], v[192:195], v[224:227], v[16:19]
	v_mfma_f32_16x16x32_bf16 v[8:11], v[200:203], v[224:227], v[8:11]
	v_mfma_f32_16x16x32_bf16 v[4:7], v[192:195], v[232:235], v[4:7]
	v_mfma_f32_16x16x32_bf16 v[0:3], v[200:203], v[232:235], v[0:3]
	v_mfma_f32_16x16x32_bf16 v[48:51], v[196:199], v[212:215], v[48:51]
	v_mfma_f32_16x16x32_bf16 v[40:43], v[204:207], v[212:215], v[40:43]
	v_mfma_f32_16x16x32_bf16 v[32:35], v[196:199], v[220:223], v[32:35]
	v_mfma_f32_16x16x32_bf16 v[24:27], v[204:207], v[220:223], v[24:27]
	v_mfma_f32_16x16x32_bf16 v[16:19], v[196:199], v[228:231], v[16:19]
	v_mfma_f32_16x16x32_bf16 v[8:11], v[204:207], v[228:231], v[8:11]
	v_mfma_f32_16x16x32_bf16 v[4:7], v[196:199], v[236:239], v[4:7]
	v_mfma_f32_16x16x32_bf16 v[0:3], v[204:207], v[236:239], v[0:3]
	s_barrier
	s_setprio 1
	s_add_i32 s3, 0, 0x18000
	v_add_u32_e32 v169, s3, v166
	s_add_i32 s8, 0, 0x1c000
	ds_read_b128 v[176:179], v169
	ds_read_b128 v[180:183], v169 offset:1024
	ds_read_b128 v[184:187], v169 offset:2048
	ds_read_b128 v[188:191], v169 offset:3072
	v_add_u32_e32 v169, s8, v166
	ds_read_b128 v[192:195], v169
	ds_read_b128 v[196:199], v169 offset:1024
	ds_read_b128 v[200:203], v169 offset:2048
	ds_read_b128 v[204:207], v169 offset:3072
	v_lshl_add_u64 v[240:241], v[240:241], 0, s[74:75]
	s_mov_b32 m0, s16
	v_lshl_add_u64 v[250:251], v[240:241], 0, v[148:149]
	ds_read_b128 v[208:211], v168 offset:32768
	ds_read_b128 v[212:215], v168 offset:33792
	ds_read_b128 v[216:219], v168 offset:34816
	ds_read_b128 v[220:223], v168 offset:35840
	ds_read_b128 v[224:227], v168 offset:36864
	ds_read_b128 v[228:231], v168 offset:37888
	ds_read_b128 v[232:235], v168 offset:38912
	ds_read_b128 v[236:239], v168 offset:39936
	global_load_lds_dwordx4 v[250:251], off
	v_lshl_add_u64 v[240:241], v[240:241], 0, v[146:147]
	s_mov_b32 m0, s17
	s_nop 0
	global_load_lds_dwordx4 v[240:241], off
	s_setprio 0
	s_waitcnt vmcnt(8) lgkmcnt(0)
	s_barrier
	v_mfma_f32_16x16x32_bf16 v[124:127], v[176:179], v[208:211], v[124:127]
	v_mfma_f32_16x16x32_bf16 v[120:123], v[184:187], v[208:211], v[120:123]
	v_mfma_f32_16x16x32_bf16 v[116:119], v[176:179], v[216:219], v[116:119]
	v_mfma_f32_16x16x32_bf16 v[108:111], v[184:187], v[216:219], v[108:111]
	v_mfma_f32_16x16x32_bf16 v[100:103], v[176:179], v[224:227], v[100:103]
	v_mfma_f32_16x16x32_bf16 v[92:95], v[184:187], v[224:227], v[92:95]
	v_mfma_f32_16x16x32_bf16 v[84:87], v[176:179], v[232:235], v[84:87]
	v_mfma_f32_16x16x32_bf16 v[76:79], v[184:187], v[232:235], v[76:79]
	v_mfma_f32_16x16x32_bf16 v[124:127], v[180:183], v[212:215], v[124:127]
	v_mfma_f32_16x16x32_bf16 v[120:123], v[188:191], v[212:215], v[120:123]
	v_mfma_f32_16x16x32_bf16 v[116:119], v[180:183], v[220:223], v[116:119]
	v_mfma_f32_16x16x32_bf16 v[108:111], v[188:191], v[220:223], v[108:111]
	v_mfma_f32_16x16x32_bf16 v[100:103], v[180:183], v[228:231], v[100:103]
	v_mfma_f32_16x16x32_bf16 v[92:95], v[188:191], v[228:231], v[92:95]
	v_mfma_f32_16x16x32_bf16 v[84:87], v[180:183], v[236:239], v[84:87]
	v_mfma_f32_16x16x32_bf16 v[76:79], v[188:191], v[236:239], v[76:79]
	v_mfma_f32_16x16x32_bf16 v[112:115], v[192:195], v[208:211], v[112:115]
	v_mfma_f32_16x16x32_bf16 v[104:107], v[200:203], v[208:211], v[104:107]
	v_mfma_f32_16x16x32_bf16 v[96:99], v[192:195], v[216:219], v[96:99]
	v_mfma_f32_16x16x32_bf16 v[88:91], v[200:203], v[216:219], v[88:91]
	v_mfma_f32_16x16x32_bf16 v[80:83], v[192:195], v[224:227], v[80:83]
	v_mfma_f32_16x16x32_bf16 v[72:75], v[200:203], v[224:227], v[72:75]
	v_mfma_f32_16x16x32_bf16 v[68:71], v[192:195], v[232:235], v[68:71]
	v_mfma_f32_16x16x32_bf16 v[64:67], v[200:203], v[232:235], v[64:67]
	v_mfma_f32_16x16x32_bf16 v[112:115], v[196:199], v[212:215], v[112:115]
	v_mfma_f32_16x16x32_bf16 v[104:107], v[204:207], v[212:215], v[104:107]
	v_mfma_f32_16x16x32_bf16 v[96:99], v[196:199], v[220:223], v[96:99]
	v_mfma_f32_16x16x32_bf16 v[88:91], v[204:207], v[220:223], v[88:91]
	v_mfma_f32_16x16x32_bf16 v[80:83], v[196:199], v[228:231], v[80:83]
	v_mfma_f32_16x16x32_bf16 v[72:75], v[204:207], v[228:231], v[72:75]
	v_mfma_f32_16x16x32_bf16 v[68:71], v[196:199], v[236:239], v[68:71]
	v_mfma_f32_16x16x32_bf16 v[64:67], v[204:207], v[236:239], v[64:67]
	s_barrier
; #define PG8_STAGE(bufoff, gbase, voff) do { _Pragma("unroll") for (int _i = 0; _i < 2; ++_i) \
;         __builtin_amdgcn_global_load_lds((const unsigned*)((const char*)(gbase) + (voff)[_i]), (PG8_LAS unsigned*)(lds + (bufoff) + ldsw + _i * 8192), 16, 0, 0); } while (0)
; #define PG8_LDA(dst, b, h) do { _Pragma("unroll") for (int m = 0; m < 4; ++m) _Pragma("unroll") for (int k = 0; k < 2; ++k) dst[m][k] = *(const PG8_LAS bf16x8*)(lds + PG8_SA(b, h) + aoff + m * 2048 + k * 1024); } while (0)
; #define PG8_MMA(ai, bj, At, Bt) do { __builtin_amdgcn_s_setprio(1); _Pragma("unroll") for (int m = 0; m < 4; ++m) _Pragma("unroll") for (int n = 0; n < 2; ++n) _Pragma("unroll") for (int k = 0; k < 2; ++k) \
;         acc[ai][bj][m][n] = __builtin_amdgcn_mfma_f32_16x16x32_bf16(Bt[n][k], At[m][k], acc[ai][bj][m][n], 0, 0, 0); __builtin_amdgcn_s_setprio(0); } while (0)
; #define PG8_WAIT_V(n) asm volatile("s_waitcnt vmcnt(" #n ")" ::: "memory")
; #define PG8_WAIT_L(n) asm volatile("s_waitcnt lgkmcnt(" #n ")" ::: "memory")
; #define PG8_BAR __builtin_amdgcn_s_barrier()
; #define PG8_SCHED __builtin_amdgcn_sched_barrier(0)
; template <class Epi, class Sched, bool ALIGN_EPI = false, bool SP2 = false>
; __device__ __forceinline__ void gemm_phase(PG8_LAS unsigned char* lds, const Gemm g, const Sched& S, const Epi& E, int tid_in) {
;     ...
;         for (int t = 0; t < nt; t += 2) {
;             const bool last = (t == nt - 2);
;             const char* a1 = cA + (size_t)(t + 1) * kstep;
;             const char* a2 = last ? nA : cA + (size_t)(t + 2) * kstep; const char* b2 = last ? nB : cB + (size_t)(t + 2) * kstep;
;             const char* a3 = a2 + kstep; const char* b3 = b2 + kstep;
;     ...
;             PG8_LDA(At, 1, 1); PG8_STAGE(PG8_SB(1, 0), b3, voffB); PG8_STAGE(PG8_SB(1, 1), b3 + hstep, voffB); PG8_STAGE(PG8_SA(1, 0), a3, voffA);
;             PG8_WAIT_V(8); PG8_WAIT_L(0); PG8_BAR; PG8_MMA(1, 0, At, B0); PG8_MMA(1, 1, At, B1); PG8_BAR; PG8_SCHED;
	s_add_i32 s3, s3, s1
	v_lshl_add_u64 v[162:163], v[162:163], 0, s[70:71]
	s_mov_b32 m0, s3
	ds_read_b128 v[208:211], v168 offset:49152
	ds_read_b128 v[212:215], v168 offset:50176
	ds_read_b128 v[216:219], v168 offset:51200
	ds_read_b128 v[220:223], v168 offset:52224
	ds_read_b128 v[224:227], v168 offset:53248
	ds_read_b128 v[228:231], v168 offset:54272
	ds_read_b128 v[232:235], v168 offset:55296
	ds_read_b128 v[236:239], v168 offset:56320
	global_load_lds_dwordx4 v[162:163], off
	v_lshl_add_u64 v[162:163], v[244:245], 0, s[70:71]
	s_add_i32 m0, s3, 0x2000
	s_add_i32 s3, s8, s1
	global_load_lds_dwordx4 v[162:163], off
	v_lshl_add_u64 v[162:163], v[242:243], 0, s[60:61]
	v_lshl_add_u64 v[240:241], v[162:163], 0, v[128:129]
	s_mov_b32 m0, s3
	v_lshl_add_u64 v[162:163], v[162:163], 0, v[144:145]
	global_load_lds_dwordx4 v[240:241], off
	s_add_i32 m0, s3, 0x2000
	s_nop 0
	global_load_lds_dwordx4 v[162:163], off
	v_lshl_add_u64 v[162:163], v[246:247], 0, s[70:71]
	s_mov_b32 m0, s18
	s_nop 0
	global_load_lds_dwordx4 v[162:163], off
	v_lshl_add_u64 v[162:163], v[248:249], 0, s[70:71]
	s_mov_b32 m0, s19
	s_nop 0
	global_load_lds_dwordx4 v[162:163], off
	s_waitcnt vmcnt(8) lgkmcnt(0)
	s_barrier
	v_mfma_f32_16x16x32_bf16 v[60:63], v[176:179], v[208:211], v[60:63]
	v_mfma_f32_16x16x32_bf16 v[56:59], v[184:187], v[208:211], v[56:59]
	v_mfma_f32_16x16x32_bf16 v[52:55], v[176:179], v[216:219], v[52:55]
	v_mfma_f32_16x16x32_bf16 v[44:47], v[184:187], v[216:219], v[44:47]
	v_mfma_f32_16x16x32_bf16 v[36:39], v[176:179], v[224:227], v[36:39]
	v_mfma_f32_16x16x32_bf16 v[28:31], v[184:187], v[224:227], v[28:31]
	v_mfma_f32_16x16x32_bf16 v[20:23], v[176:179], v[232:235], v[20:23]
	v_mfma_f32_16x16x32_bf16 v[12:15], v[184:187], v[232:235], v[12:15]
	v_mfma_f32_16x16x32_bf16 v[60:63], v[180:183], v[212:215], v[60:63]
	v_mfma_f32_16x16x32_bf16 v[56:59], v[188:191], v[212:215], v[56:59]
	v_mfma_f32_16x16x32_bf16 v[52:55], v[180:183], v[220:223], v[52:55]
	v_mfma_f32_16x16x32_bf16 v[44:47], v[188:191], v[220:223], v[44:47]
	v_mfma_f32_16x16x32_bf16 v[36:39], v[180:183], v[228:231], v[36:39]
	v_mfma_f32_16x16x32_bf16 v[28:31], v[188:191], v[228:231], v[28:31]
	v_mfma_f32_16x16x32_bf16 v[20:23], v[180:183], v[236:239], v[20:23]
	v_mfma_f32_16x16x32_bf16 v[12:15], v[188:191], v[236:239], v[12:15]
	v_mfma_f32_16x16x32_bf16 v[48:51], v[192:195], v[208:211], v[48:51]
	v_mfma_f32_16x16x32_bf16 v[40:43], v[200:203], v[208:211], v[40:43]
	v_mfma_f32_16x16x32_bf16 v[32:35], v[192:195], v[216:219], v[32:35]
	v_mfma_f32_16x16x32_bf16 v[24:27], v[200:203], v[216:219], v[24:27]
	v_mfma_f32_16x16x32_bf16 v[16:19], v[192:195], v[224:227], v[16:19]
	v_mfma_f32_16x16x32_bf16 v[8:11], v[200:203], v[224:227], v[8:11]
	v_mfma_f32_16x16x32_bf16 v[4:7], v[192:195], v[232:235], v[4:7]
	v_mfma_f32_16x16x32_bf16 v[0:3], v[200:203], v[232:235], v[0:3]
	v_mfma_f32_16x16x32_bf16 v[48:51], v[196:199], v[212:215], v[48:51]
	v_mfma_f32_16x16x32_bf16 v[40:43], v[204:207], v[212:215], v[40:43]
	v_mfma_f32_16x16x32_bf16 v[32:35], v[196:199], v[220:223], v[32:35]
	v_mfma_f32_16x16x32_bf16 v[24:27], v[204:207], v[220:223], v[24:27]
	v_mfma_f32_16x16x32_bf16 v[16:19], v[196:199], v[228:231], v[16:19]
	v_mfma_f32_16x16x32_bf16 v[8:11], v[204:207], v[228:231], v[8:11]
	v_mfma_f32_16x16x32_bf16 v[4:7], v[196:199], v[236:239], v[4:7]
	v_mfma_f32_16x16x32_bf16 v[0:3], v[204:207], v[236:239], v[0:3]
	s_barrier
	s_setprio 1
	s_add_i32 s2, s2, 2
	v_lshl_add_u64 v[160:161], v[160:161], 0, s[82:83]
	s_cmpk_gt_u32 s2, 0x55
	v_mov_b64_e32 v[162:163], v[164:165]
	s_cbranch_scc0 .LBB0_683
	s_setprio 0
	s_and_b64 vcc, exec, s[12:13]
	s_cbranch_vccz .LBB0_686
	s_barrier
